# stack: fox loop-top interleave, fox cumsum loads fetched once, norm load hoisted to item start, P4 gate vectors loaded once per chunk
# speedup vs baseline: 1.0046x; 1.0046x over previous
.LBB0_852:
	s_movk_i32 s98, 0x180
	s_and_b64 s[100:101], s[36:37], exec
	s_cselect_b32 s98, s98, 0x200
	s_add_u32 s100, s66, s98
	s_addc_u32 s101, s67, 0
	s_lshl_b32 s98, s0, 3
	s_ashr_i32 s99, s98, 31
	s_add_u32 s100, s100, s98
	s_addc_u32 s101, s101, s99
	global_load_dwordx2 v[252:253], v1, s[100:101]
	v_ashrrev_i32_e32 v218, 7, v6
	v_and_b32_e32 v176, 31, v6
	v_lshlrev_b32_e32 v165, 5, v218
	v_or_b32_e32 v164, v165, v176
	s_add_i32 s1, s48, -1
	v_min_i32_e32 v66, s1, v164
	v_ashrrev_i32_e32 v0, 6, v6
	v_ashrrev_i32_e32 v67, 31, v66
	v_and_b32_e32 v217, 1, v0
	v_lshlrev_b64 v[2:3], 8, v[66:67]
	s_waitcnt vmcnt(5)
	v_bfe_u32 v138, v6, 5, 1
	v_lshl_add_u64 v[2:3], s[4:5], 0, v[2:3]
	v_lshlrev_b32_e32 v68, 7, v217
	v_mov_b32_e32 v69, v1
	v_lshl_add_u64 v[2:3], v[2:3], 0, v[68:69]
	v_lshlrev_b32_e32 v70, 4, v138
	v_mov_b32_e32 v71, v1
	v_lshl_add_u64 v[2:3], v[2:3], 0, v[70:71]
	global_load_dwordx4 v[112:115], v[2:3], off
	global_load_dwordx4 v[116:119], v[2:3], off offset:32
	global_load_dwordx4 v[120:123], v[2:3], off offset:64
	global_load_dwordx4 v[124:127], v[2:3], off offset:96
	v_and_b32_e32 v171, 63, v6
	v_cmp_eq_u32_e32 vcc, 0, v171
	s_waitcnt vmcnt(3)
	v_and_b32_e32 v3, 0xffff0000, v112
	v_lshlrev_b32_e32 v2, 16, v112
	v_mul_f32_e32 v3, v3, v3
	v_fmac_f32_e32 v3, v2, v2
	v_lshlrev_b32_e32 v2, 16, v113
	v_fmac_f32_e32 v3, v2, v2
	v_and_b32_e32 v2, 0xffff0000, v113
	v_fmac_f32_e32 v3, v2, v2
	v_lshlrev_b32_e32 v2, 16, v114
	v_fmac_f32_e32 v3, v2, v2
	v_and_b32_e32 v2, 0xffff0000, v114
	v_fmac_f32_e32 v3, v2, v2
	v_lshlrev_b32_e32 v2, 16, v115
	v_fmac_f32_e32 v3, v2, v2
	v_and_b32_e32 v2, 0xffff0000, v115
	s_waitcnt vmcnt(2)
	v_and_b32_e32 v4, 0xffff0000, v116
	v_fmac_f32_e32 v3, v2, v2
	v_lshlrev_b32_e32 v2, 16, v116
	v_mul_f32_e32 v4, v4, v4
	v_fmac_f32_e32 v4, v2, v2
	v_lshlrev_b32_e32 v2, 16, v117
	v_fmac_f32_e32 v4, v2, v2
	v_and_b32_e32 v2, 0xffff0000, v117
	v_fmac_f32_e32 v4, v2, v2
	v_lshlrev_b32_e32 v2, 16, v118
	v_fmac_f32_e32 v4, v2, v2
	v_and_b32_e32 v2, 0xffff0000, v118
	v_fmac_f32_e32 v4, v2, v2
	v_lshlrev_b32_e32 v2, 16, v119
	v_fmac_f32_e32 v4, v2, v2
	v_and_b32_e32 v2, 0xffff0000, v119
	v_fmac_f32_e32 v4, v2, v2
	v_add_f32_e32 v2, v3, v4
	s_waitcnt vmcnt(1)
	v_and_b32_e32 v4, 0xffff0000, v120
	v_lshlrev_b32_e32 v3, 16, v120
	v_mul_f32_e32 v4, v4, v4
	v_fmac_f32_e32 v4, v3, v3
	v_lshlrev_b32_e32 v3, 16, v121
	v_fmac_f32_e32 v4, v3, v3
	v_and_b32_e32 v3, 0xffff0000, v121
	v_fmac_f32_e32 v4, v3, v3
	v_lshlrev_b32_e32 v3, 16, v122
	v_fmac_f32_e32 v4, v3, v3
	v_and_b32_e32 v3, 0xffff0000, v122
	v_fmac_f32_e32 v4, v3, v3
	v_lshlrev_b32_e32 v3, 16, v123
	v_fmac_f32_e32 v4, v3, v3
	v_and_b32_e32 v3, 0xffff0000, v123
	v_fmac_f32_e32 v4, v3, v3
	v_add_f32_e32 v2, v2, v4
	s_waitcnt vmcnt(0)
	v_and_b32_e32 v4, 0xffff0000, v124
	v_lshlrev_b32_e32 v3, 16, v124
	v_mul_f32_e32 v4, v4, v4
	v_fmac_f32_e32 v4, v3, v3
	v_lshlrev_b32_e32 v3, 16, v125
	v_fmac_f32_e32 v4, v3, v3
	v_and_b32_e32 v3, 0xffff0000, v125
	v_fmac_f32_e32 v4, v3, v3
	v_lshlrev_b32_e32 v3, 16, v126
	v_fmac_f32_e32 v4, v3, v3
	v_and_b32_e32 v3, 0xffff0000, v126
	v_fmac_f32_e32 v4, v3, v3
	v_lshlrev_b32_e32 v3, 16, v127
	v_fmac_f32_e32 v4, v3, v3
	v_and_b32_e32 v3, 0xffff0000, v127
	v_fmac_f32_e32 v4, v3, v3
	v_add_f32_e32 v2, v2, v4
	ds_bpermute_b32 v3, v205, v2
	s_waitcnt lgkmcnt(0)
	v_add_f32_e32 v2, v2, v3
	ds_bpermute_b32 v3, v207, v2
	s_waitcnt lgkmcnt(0)
	v_max_f32_e32 v3, v3, v3
	v_max_f32_e32 v2, v2, v3
	ds_bpermute_b32 v3, v208, v2
	s_waitcnt lgkmcnt(0)
	v_max_f32_e32 v3, v3, v3
	v_max_f32_e32 v2, v2, v3
	ds_bpermute_b32 v3, v209, v2
	s_waitcnt lgkmcnt(0)
	v_max_f32_e32 v3, v3, v3
	v_max_f32_e32 v2, v2, v3
	ds_bpermute_b32 v3, v210, v2
	s_waitcnt lgkmcnt(0)
	v_max_f32_e32 v3, v3, v3
	v_max_f32_e32 v2, v2, v3
	ds_bpermute_b32 v3, v206, v2
	s_and_saveexec_b64 s[4:5], vcc
	s_cbranch_execz .LBB0_854
	s_waitcnt lgkmcnt(0)
	v_max_f32_e32 v3, v3, v3
	v_max_f32_e32 v2, v2, v2
	v_lshl_add_u32 v0, v0, 2, v203
	v_max_f32_e32 v2, v2, v3
	ds_write_b32 v0, v2
.LBB0_854:
	s_or_b64 exec, exec, s[4:5]
	s_add_i32 s1, s54, 1
	v_cvt_f32_i32_e32 v0, s1
	s_add_i32 s46, s51, 63
	s_lshr_b32 s62, s46, 6
	s_and_b64 s[4:5], s[36:37], exec
	s_movk_i32 s1, 0x180
	v_mul_f32_e32 v0, -2.0, v0
	s_waitcnt lgkmcnt(0)
	s_barrier
	ds_read_b128 v[2:5], v203
	s_cselect_b32 s1, s1, 0x200
	v_exp_f32_e32 v0, v0
	s_add_u32 s4, s66, s1
	s_addc_u32 s5, s67, 0
	s_lshl_b32 s0, s0, 1
	s_ashr_i32 s1, s0, 31
	s_lshl_b64 s[0:1], s[0:1], 2
	v_mul_f32_e32 v166, 0x3fb8aa3b, v0
	s_waitcnt lgkmcnt(0)
	v_max_f32_e32 v0, v5, v5
	v_max_f32_e32 v4, v4, v4
	s_add_u32 s0, s4, s0
	v_max_f32_e32 v0, v4, v0
	s_addc_u32 s1, s5, s1
	v_max3_f32 v0, v2, v3, v0
	s_nop 0
	v_ashrrev_i32_e32 v10, 4, v6
	s_and_b32 s6, s46, 0x7fffffc0
	v_ashrrev_i32_e32 v8, 3, v6
	v_add_u32_e32 v7, s52, v66
	v_add_u32_e32 v9, 32, v8
	v_add_u32_e32 v11, 64, v8
	v_add_u32_e32 v12, 0x60, v8
	v_add_f32_e32 v167, v166, v166
	v_mul_lo_u32 v69, v10, s91
	v_mul_lo_u32 v71, v8, s92
	v_lshlrev_b32_e32 v139, 2, v138
	v_mul_u32_u24_e32 v140, 0x110, v176
	s_waitcnt vmcnt(0)
	v_mov_b32_e32 v2, v252
	v_mov_b32_e32 v3, v253
	v_max_f32_e32 v3, v3, v3
	v_max_f32_e32 v2, v2, v2
	v_max_f32_e32 v2, v2, v3
	v_mul_f32_e32 v0, v0, v2
	v_cmp_gt_f32_e32 vcc, s88, v0
	v_mul_f32_e32 v2, 0x4f800000, v0
	s_nop 0
	v_cndmask_b32_e32 v0, v0, v2, vcc
	v_sqrt_f32_e32 v2, v0
	s_nop 0
	v_add_u32_e32 v3, -1, v2
	v_fma_f32 v4, -v3, v2, v0
	v_cmp_ge_f32_e64 s[0:1], 0, v4
	v_add_u32_e32 v4, 1, v2
	s_nop 0
	v_cndmask_b32_e64 v3, v2, v3, s[0:1]
	v_fma_f32 v2, -v4, v2, v0
	v_cmp_lt_f32_e64 s[0:1], 0, v2
	s_nop 1
	v_cndmask_b32_e64 v2, v3, v4, s[0:1]
	v_mul_f32_e32 v3, 0x37800000, v2
	v_cndmask_b32_e32 v2, v2, v3, vcc
	v_cmp_class_f32_e32 vcc, v0, v211
	s_nop 1
	v_cndmask_b32_e32 v0, v2, v0, vcc
	v_fma_f32 v67, v0, s89, 0.5
	v_lshlrev_b32_e32 v2, 3, v6
	v_cmp_lt_f32_e64 s[4:5], s90, v67
	v_and_b32_e32 v0, 0x78, v2
	v_and_b32_e32 v72, 56, v2
	v_add_u32_e32 v2, s6, v10
	s_and_b64 vcc, exec, s[4:5]
	v_readfirstlane_b32 s34, v0
	v_ashrrev_i32_e32 v3, 31, v2
	v_lshlrev_b32_e32 v76, 1, v0
	v_lshlrev_b32_e32 v74, 1, v72
	s_cbranch_vccnz .LBB0_856
	s_lshl_b32 s34, s62, 6
	v_lshlrev_b64 v[4:5], 8, v[2:3]
	v_add_u32_e32 v13, s34, v10
	v_lshl_add_u64 v[80:81], v[4:5], 0, s[16:17]
	v_lshl_add_u64 v[84:85], v[4:5], 0, s[18:19]
	v_lshl_add_u64 v[88:89], v[4:5], 0, s[20:21]
	v_add_u32_e32 v4, 0xffffff80, v13
	v_ashrrev_i32_e32 v5, 31, v4
	v_lshlrev_b64 v[92:93], 8, v[4:5]
	v_add_u32_e32 v4, 0xffffffb0, v13
	v_ashrrev_i32_e32 v5, 31, v4
	v_lshlrev_b64 v[96:97], 8, v[4:5]
	v_add_u32_e32 v4, 0xffffffa0, v13
	v_mad_i64_i32 v[78:79], s[0:1], s44, v8, 0
	v_mad_i64_i32 v[82:83], s[0:1], s44, v9, 0
	v_mad_i64_i32 v[86:87], s[0:1], s44, v11, 0
	v_mad_i64_i32 v[90:91], s[0:1], s44, v12, 0
	v_ashrrev_i32_e32 v5, 31, v4
	s_lshl_b64 s[0:1], s[46:47], 1
	v_lshlrev_b64 v[98:99], 8, v[4:5]
	v_add_u32_e32 v4, 0xffffff90, v13
	v_mul_lo_u32 v224, v10, s91
	v_mul_lo_u32 v226, v8, s92
	s_sub_i32 s45, s51, 64
	v_lshlrev_b32_e32 v170, 2, v138
	s_and_b32 s31, s1, 1
	s_and_b32 s30, s0, 0xffffff80
	v_ashrrev_i32_e32 v5, 31, v4
	s_add_i32 s53, s62, 1
	s_add_i32 s63, s52, 64
	v_mov_b32_e32 v73, v1
	v_lshlrev_b32_e32 v225, 1, v0
	v_lshlrev_b32_e32 v227, 1, v72
	v_add_u32_e32 v162, 0x1100, v224
	v_add_u32_e32 v219, 0x1100, v226
	v_add_u32_e32 v220, 0x2200, v224
	v_add_u32_e32 v221, 0x2200, v226
	v_add_u32_e32 v222, 0x3300, v224
	v_add_u32_e32 v223, 0x3300, v226
	v_sub_u32_e32 v75, v170, v7
	v_fma_f32 v168, 2.0, v166, v166
	v_mul_f32_e32 v169, 0x41000000, v166
	v_lshlrev_b32_e32 v228, 7, v217
	v_lshlrev_b32_e32 v229, 4, v138
	v_mul_u32_u24_e32 v230, 0x110, v176
	v_lshlrev_b64 v[100:101], 8, v[4:5]
	s_mov_b64 s[0:1], 0
	v_mov_b32_e32 v13, s63
	v_mov_b32_e32 v232, s53
	v_mov_b64_e32 v[4:5], s[30:31]
	v_mov_b32_e32 v231, s45
	v_mov_b64_e32 v[94:95], v[0:1]
	s_branch .LBB0_857

.LBB0_891:
	s_and_b64 s[100:101], s[36:37], exec
	s_cselect_b32 s98, 0, 32
	s_add_i32 s98, s44, s98
	s_ashr_i32 s99, s98, 31
	s_lshl_b64 s[98:99], s[98:99], 2
	s_add_u32 s98, s66, s98
	s_addc_u32 s99, s67, s99
	global_load_dword v252, v1, s[98:99]
	s_add_i32 s43, s45, s63
	v_lshlrev_b32_e32 v8, 5, v14
	v_cmp_gt_i32_e64 s[4:5], s43, v8
	v_mov_b32_e32 v4, 0
	v_ashrrev_i32_e32 v9, 31, v8
	v_or_b32_e32 v13, 4, v8
	s_and_saveexec_b64 s[0:1], s[4:5]
	s_cbranch_execz .LBB0_907
	v_lshl_add_u64 v[2:3], v[8:9], 2, s[48:49]
	global_load_dwordx4 v[4:7], v[2:3], off
	global_load_dwordx4 v[20:23], v[2:3], off offset:16
	global_load_dwordx4 v[24:27], v[2:3], off offset:32
	global_load_dwordx4 v[28:31], v[2:3], off offset:48
	global_load_dwordx4 v[32:35], v[2:3], off offset:64
	global_load_dwordx4 v[36:39], v[2:3], off offset:80
	global_load_dwordx4 v[40:43], v[2:3], off offset:96
	global_load_dwordx4 v[44:47], v[2:3], off offset:112
	v_cmp_gt_i32_e32 vcc, s43, v13
	s_waitcnt vmcnt(0)
	v_mov_b32_e32 v48, v4
	v_mov_b32_e32 v49, v5
	v_mov_b32_e32 v50, v6
	v_mov_b32_e32 v51, v7
	v_mov_b32_e32 v10, v5
	v_mov_b32_e32 v11, v6
	v_mov_b32_e32 v5, v7
	v_pk_add_f32 v[4:5], v[10:11], v[4:5]
	s_nop 0
	v_add_f32_e32 v0, v4, v5
	v_add_f32_e32 v4, 0, v0
	s_and_saveexec_b64 s[50:51], vcc
	s_cbranch_execz .LBB0_894
	v_mov_b32_e32 v16, v20
	v_mov_b32_e32 v17, v21
	v_mov_b32_e32 v18, v22
	v_mov_b32_e32 v19, v23
	v_mov_b32_e32 v6, v17
	v_mov_b32_e32 v7, v18
	v_mov_b32_e32 v17, v19
	v_pk_add_f32 v[6:7], v[6:7], v[16:17]
	s_nop 0
	v_add_f32_e32 v0, v6, v7
	v_add_f32_e32 v4, v4, v0
.LBB0_894:
	s_or_b64 exec, exec, s[50:51]
	v_or_b32_e32 v0, 8, v8
	v_cmp_gt_i32_e32 vcc, s43, v0
	s_and_saveexec_b64 s[50:51], vcc
	s_cbranch_execz .LBB0_896
	v_mov_b32_e32 v16, v24
	v_mov_b32_e32 v17, v25
	v_mov_b32_e32 v18, v26
	v_mov_b32_e32 v19, v27
	v_mov_b32_e32 v6, v17
	v_mov_b32_e32 v7, v18
	v_mov_b32_e32 v17, v19
	v_pk_add_f32 v[6:7], v[6:7], v[16:17]
	s_nop 0
	v_add_f32_e32 v0, v6, v7
	v_add_f32_e32 v4, v4, v0
.LBB0_896:
	s_or_b64 exec, exec, s[50:51]
	v_or_b32_e32 v0, 12, v8
	v_cmp_gt_i32_e32 vcc, s43, v0
	s_and_saveexec_b64 s[50:51], vcc
	s_cbranch_execz .LBB0_898
	v_mov_b32_e32 v16, v28
	v_mov_b32_e32 v17, v29
	v_mov_b32_e32 v18, v30
	v_mov_b32_e32 v19, v31
	v_mov_b32_e32 v6, v17
	v_mov_b32_e32 v7, v18
	v_mov_b32_e32 v17, v19
	v_pk_add_f32 v[6:7], v[6:7], v[16:17]
	s_nop 0
	v_add_f32_e32 v0, v6, v7
	v_add_f32_e32 v4, v4, v0
.LBB0_898:
	s_or_b64 exec, exec, s[50:51]
	v_or_b32_e32 v0, 16, v8
	v_cmp_gt_i32_e32 vcc, s43, v0
	s_and_saveexec_b64 s[50:51], vcc
	s_cbranch_execz .LBB0_900
	v_mov_b32_e32 v16, v32
	v_mov_b32_e32 v17, v33
	v_mov_b32_e32 v18, v34
	v_mov_b32_e32 v19, v35
	v_mov_b32_e32 v6, v17
	v_mov_b32_e32 v7, v18
	v_mov_b32_e32 v17, v19
	v_pk_add_f32 v[6:7], v[6:7], v[16:17]
	s_nop 0
	v_add_f32_e32 v0, v6, v7
	v_add_f32_e32 v4, v4, v0
.LBB0_900:
	s_or_b64 exec, exec, s[50:51]
	v_or_b32_e32 v0, 20, v8
	v_cmp_gt_i32_e32 vcc, s43, v0
	s_and_saveexec_b64 s[50:51], vcc
	s_cbranch_execz .LBB0_902
	v_mov_b32_e32 v16, v36
	v_mov_b32_e32 v17, v37
	v_mov_b32_e32 v18, v38
	v_mov_b32_e32 v19, v39
	v_mov_b32_e32 v6, v17
	v_mov_b32_e32 v7, v18
	v_mov_b32_e32 v17, v19
	v_pk_add_f32 v[6:7], v[6:7], v[16:17]
	s_nop 0
	v_add_f32_e32 v0, v6, v7
	v_add_f32_e32 v4, v4, v0
.LBB0_902:
	s_or_b64 exec, exec, s[50:51]
	v_or_b32_e32 v0, 24, v8
	v_cmp_gt_i32_e32 vcc, s43, v0
	s_and_saveexec_b64 s[50:51], vcc
	s_cbranch_execz .LBB0_904
	v_mov_b32_e32 v16, v40
	v_mov_b32_e32 v17, v41
	v_mov_b32_e32 v18, v42
	v_mov_b32_e32 v19, v43
	v_mov_b32_e32 v6, v17
	v_mov_b32_e32 v7, v18
	v_mov_b32_e32 v17, v19
	v_pk_add_f32 v[6:7], v[6:7], v[16:17]
	s_nop 0
	v_add_f32_e32 v0, v6, v7
	v_add_f32_e32 v4, v4, v0
.LBB0_904:
	s_or_b64 exec, exec, s[50:51]
	v_or_b32_e32 v0, 28, v8
	v_cmp_gt_i32_e32 vcc, s43, v0
	s_and_saveexec_b64 s[50:51], vcc
	s_cbranch_execz .LBB0_906
	v_mov_b32_e32 v16, v44
	v_mov_b32_e32 v17, v45
	v_mov_b32_e32 v18, v46
	v_mov_b32_e32 v19, v47
	v_mov_b32_e32 v2, v17
	v_mov_b32_e32 v3, v18
	v_mov_b32_e32 v17, v19
	v_pk_add_f32 v[2:3], v[2:3], v[16:17]
	s_nop 0
	v_add_f32_e32 v0, v2, v3
	v_add_f32_e32 v4, v4, v0

.LBB0_913:
	s_or_b64 exec, exec, s[50:51]
	s_add_i32 s6, s43, 63
	s_and_b32 s52, s6, 0x7fc0
	v_cmp_gt_i32_e64 s[0:1], s52, v8
	s_and_saveexec_b64 s[50:51], s[0:1]
	s_cbranch_execz .LBB0_931
	v_lshl_add_u64 v[10:11], v[8:9], 2, s[48:49]
	v_mov_b32_e32 v2, 0
	v_mov_b32_e32 v4, 0
	v_mov_b32_e32 v5, 0
	v_mov_b32_e32 v6, 0
	v_mov_b32_e32 v7, 0
	s_and_saveexec_b64 s[0:1], s[4:5]
	s_cbranch_execz .LBB0_916
	v_mov_b32_e32 v4, v48
	v_mov_b32_e32 v5, v49
	v_mov_b32_e32 v6, v50
	v_mov_b32_e32 v7, v51
.LBB0_916:
	s_or_b64 exec, exec, s[0:1]
	s_waitcnt vmcnt(0)
	v_add_f32_e32 v4, v3, v4
	v_add_f32_e32 v5, v5, v4
	v_add_f32_e32 v6, v6, v5
	v_add_f32_e32 v7, v7, v6
	v_lshlrev_b32_e32 v9, 2, v8
	v_pk_mul_f32 v[16:17], v[4:5], s[8:9] op_sel_hi:[1,0]
	v_pk_mul_f32 v[18:19], v[6:7], s[8:9] op_sel_hi:[1,0]
	v_cmp_gt_i32_e64 s[0:1], s43, v13
	v_mov_b32_e32 v3, 0
	v_mov_b32_e32 v4, 0
	v_mov_b32_e32 v5, 0
	ds_write_b128 v9, v[16:19]
	s_and_saveexec_b64 s[4:5], s[0:1]
	s_cbranch_execz .LBB0_918
	v_mov_b32_e32 v2, v20
	v_mov_b32_e32 v3, v21
	v_mov_b32_e32 v4, v22
	v_mov_b32_e32 v5, v23
.LBB0_918:
	s_or_b64 exec, exec, s[4:5]
	s_waitcnt vmcnt(0)
	v_add_f32_e32 v6, v7, v2
	v_add_f32_e32 v7, v3, v6
	v_add_f32_e32 v2, v4, v7
	v_add_f32_e32 v3, v5, v2
	v_pk_mul_f32 v[4:5], v[6:7], s[8:9] op_sel_hi:[1,0]
	v_pk_mul_f32 v[6:7], v[2:3], s[8:9] op_sel_hi:[1,0]
	v_or_b32_e32 v2, 8, v8
	ds_write_b128 v9, v[4:7] offset:16
	v_cmp_gt_i32_e64 s[0:1], s43, v2
	v_mov_b32_e32 v2, 0
	v_mov_b32_e32 v4, 0
	v_mov_b32_e32 v5, 0
	v_mov_b32_e32 v6, 0
	v_mov_b32_e32 v7, 0
	s_and_saveexec_b64 s[4:5], s[0:1]
	s_cbranch_execz .LBB0_920
	v_mov_b32_e32 v4, v24
	v_mov_b32_e32 v5, v25
	v_mov_b32_e32 v6, v26
	v_mov_b32_e32 v7, v27
.LBB0_920:
	s_or_b64 exec, exec, s[4:5]
	s_waitcnt vmcnt(0)
	v_add_f32_e32 v4, v3, v4
	v_add_f32_e32 v5, v5, v4
	v_add_f32_e32 v6, v6, v5
	v_add_f32_e32 v7, v7, v6
	v_or_b32_e32 v3, 12, v8
	v_pk_mul_f32 v[16:17], v[4:5], s[8:9] op_sel_hi:[1,0]
	v_pk_mul_f32 v[18:19], v[6:7], s[8:9] op_sel_hi:[1,0]
	v_cmp_gt_i32_e64 s[0:1], s43, v3
	v_mov_b32_e32 v3, 0
	v_mov_b32_e32 v4, 0
	v_mov_b32_e32 v5, 0
	ds_write_b128 v9, v[16:19] offset:32
	s_and_saveexec_b64 s[4:5], s[0:1]
	s_cbranch_execz .LBB0_922
	v_mov_b32_e32 v2, v28
	v_mov_b32_e32 v3, v29
	v_mov_b32_e32 v4, v30
	v_mov_b32_e32 v5, v31
.LBB0_922:
	s_or_b64 exec, exec, s[4:5]
	s_waitcnt vmcnt(0)
	v_add_f32_e32 v6, v7, v2
	v_add_f32_e32 v7, v3, v6
	v_add_f32_e32 v2, v4, v7
	v_add_f32_e32 v3, v5, v2
	v_pk_mul_f32 v[4:5], v[6:7], s[8:9] op_sel_hi:[1,0]
	v_pk_mul_f32 v[6:7], v[2:3], s[8:9] op_sel_hi:[1,0]
	v_or_b32_e32 v2, 16, v8
	ds_write_b128 v9, v[4:7] offset:48
	v_cmp_gt_i32_e64 s[0:1], s43, v2
	v_mov_b32_e32 v2, 0
	v_mov_b32_e32 v4, 0
	v_mov_b32_e32 v5, 0
	v_mov_b32_e32 v6, 0
	v_mov_b32_e32 v7, 0
	s_and_saveexec_b64 s[4:5], s[0:1]
	s_cbranch_execz .LBB0_924
	v_mov_b32_e32 v4, v32
	v_mov_b32_e32 v5, v33
	v_mov_b32_e32 v6, v34
	v_mov_b32_e32 v7, v35
.LBB0_924:
	s_or_b64 exec, exec, s[4:5]
	s_waitcnt vmcnt(0)
	v_add_f32_e32 v4, v3, v4
	v_add_f32_e32 v5, v5, v4
	v_add_f32_e32 v6, v6, v5
	v_add_f32_e32 v7, v7, v6
	v_or_b32_e32 v3, 20, v8
	v_pk_mul_f32 v[16:17], v[4:5], s[8:9] op_sel_hi:[1,0]
	v_pk_mul_f32 v[18:19], v[6:7], s[8:9] op_sel_hi:[1,0]
	v_cmp_gt_i32_e64 s[0:1], s43, v3
	v_mov_b32_e32 v3, 0
	v_mov_b32_e32 v4, 0
	v_mov_b32_e32 v5, 0
	ds_write_b128 v9, v[16:19] offset:64
	s_and_saveexec_b64 s[4:5], s[0:1]
	s_cbranch_execz .LBB0_926
	v_mov_b32_e32 v2, v36
	v_mov_b32_e32 v3, v37
	v_mov_b32_e32 v4, v38
	v_mov_b32_e32 v5, v39
.LBB0_926:
	s_or_b64 exec, exec, s[4:5]
	s_waitcnt vmcnt(0)
	v_add_f32_e32 v6, v7, v2
	v_add_f32_e32 v7, v3, v6
	v_add_f32_e32 v2, v4, v7
	v_add_f32_e32 v3, v5, v2
	v_pk_mul_f32 v[4:5], v[6:7], s[8:9] op_sel_hi:[1,0]
	v_pk_mul_f32 v[6:7], v[2:3], s[8:9] op_sel_hi:[1,0]
	v_or_b32_e32 v2, 24, v8
	ds_write_b128 v9, v[4:7] offset:80
	v_cmp_gt_i32_e64 s[0:1], s43, v2
	v_mov_b32_e32 v2, 0
	v_mov_b32_e32 v4, 0
	v_mov_b32_e32 v5, 0
	v_mov_b32_e32 v6, 0
	v_mov_b32_e32 v7, 0
	s_and_saveexec_b64 s[4:5], s[0:1]
	s_cbranch_execz .LBB0_928
	v_mov_b32_e32 v4, v40
	v_mov_b32_e32 v5, v41
	v_mov_b32_e32 v6, v42
	v_mov_b32_e32 v7, v43
.LBB0_928:
	s_or_b64 exec, exec, s[4:5]
	s_waitcnt vmcnt(0)
	v_add_f32_e32 v4, v3, v4
	v_add_f32_e32 v5, v5, v4
	v_add_f32_e32 v6, v6, v5
	v_add_f32_e32 v7, v7, v6
	v_or_b32_e32 v3, 28, v8
	v_pk_mul_f32 v[16:17], v[4:5], s[8:9] op_sel_hi:[1,0]
	v_pk_mul_f32 v[18:19], v[6:7], s[8:9] op_sel_hi:[1,0]
	v_cmp_gt_i32_e64 s[0:1], s43, v3
	v_mov_b32_e32 v3, 0
	v_mov_b32_e32 v4, 0
	v_mov_b32_e32 v5, 0
	ds_write_b128 v9, v[16:19] offset:96
	s_and_saveexec_b64 s[4:5], s[0:1]
	s_cbranch_execz .LBB0_930
	v_mov_b32_e32 v2, v44
	v_mov_b32_e32 v3, v45
	v_mov_b32_e32 v4, v46
	v_mov_b32_e32 v5, v47

.LBB0_933:
	s_or_b64 exec, exec, s[0:1]
	s_lshr_b32 s46, s6, 6
	s_and_b64 s[0:1], s[36:37], exec
	s_waitcnt lgkmcnt(0)
	s_barrier
	ds_read_b128 v[4:7], v214
	s_cselect_b32 s0, 0, 32
	s_add_i32 s0, s44, s0
	s_ashr_i32 s1, s0, 31
	s_lshl_b64 s[0:1], s[0:1], 2
	s_add_u32 s0, s66, s0
	s_waitcnt lgkmcnt(0)
	v_max_f32_e32 v0, v7, v7
	v_max_f32_e32 v3, v6, v6
	s_addc_u32 s1, s67, s1
	v_max_f32_e32 v0, v3, v0
	s_nop 0
	v_max3_f32 v0, v4, v5, v0
	v_ashrrev_i32_e32 v15, 3, v14
	v_add_u32_e32 v16, 32, v15
	v_mul_lo_u32 v109, v15, s94
	v_mul_lo_u32 v110, v15, s92
	v_lshlrev_b32_e32 v111, 2, v108
	v_mul_u32_u24_e32 v112, 0x90, v118
	s_waitcnt vmcnt(0)
	v_mov_b32_e32 v3, v252
	v_mul_f32_e32 v0, v3, v0
	v_cmp_gt_f32_e32 vcc, s88, v0
	v_mul_f32_e32 v3, 0x4f800000, v0
	s_nop 0
	v_cndmask_b32_e32 v0, v0, v3, vcc
	v_sqrt_f32_e32 v3, v0
	s_nop 0
	v_add_u32_e32 v4, -1, v3
	v_fma_f32 v5, -v4, v3, v0
	v_cmp_ge_f32_e64 s[0:1], 0, v5
	v_add_u32_e32 v5, 1, v3
	s_nop 0
	v_cndmask_b32_e64 v4, v3, v4, s[0:1]
	v_fma_f32 v3, -v5, v3, v0
	v_cmp_lt_f32_e64 s[0:1], 0, v3
	s_nop 1
	v_cndmask_b32_e64 v3, v4, v5, s[0:1]
	v_mul_f32_e32 v4, 0x37800000, v3
	v_cndmask_b32_e32 v3, v3, v4, vcc
	v_cmp_class_f32_e32 vcc, v0, v211
	s_lshl_b32 s0, s63, 2
	s_nop 0
	v_cndmask_b32_e32 v0, v3, v0, vcc
	v_fma_f32 v67, v0, s89, 0.5
	v_mov_b32_e32 v0, s0
	ds_read_b32 v127, v0
	v_lshlrev_b32_e32 v0, 3, v14
	v_cmp_lt_f32_e64 s[4:5], s90, v67
	v_and_b32_e32 v68, 56, v0
	v_readfirstlane_b32 s44, v0
	v_add_u32_e32 v0, s52, v15
	s_mov_b64 s[0:1], -1
	s_and_b64 vcc, exec, s[4:5]
	v_subrev_u32_e32 v4, 32, v0
	v_lshlrev_b32_e32 v70, 1, v68
	s_cbranch_vccnz .LBB0_935
	s_lshl_b32 s44, s46, 6
	v_add_u32_e32 v3, s44, v15
	v_mad_i64_i32 v[72:73], s[0:1], s42, v15, 0
	v_mad_i64_i32 v[76:77], s[0:1], s42, v16, 0
	v_add_u32_e32 v6, 0xffffff80, v3
	s_add_i32 s6, s43, 48
	v_ashrrev_i32_e32 v7, 31, v6
	s_lshl_b64 s[0:1], s[6:7], 1
	v_lshlrev_b64 v[78:79], 7, v[6:7]
	s_add_u32 s0, s0, 30
	v_add_u32_e32 v6, 0xffffffa0, v3
	v_ashrrev_i32_e32 v5, 31, v4
	v_mul_lo_u32 v132, v15, s94
	v_mul_lo_u32 v134, v15, s92
	s_addc_u32 s31, s1, 0
	s_and_b32 s30, s0, 0xffffff80
	v_ashrrev_i32_e32 v7, 31, v6
	s_add_i32 s6, s46, 1
	s_lshl_b32 s36, s46, 8
	v_mov_b32_e32 v69, v1
	v_lshlrev_b64 v[74:75], 7, v[4:5]
	v_lshlrev_b32_e32 v133, 1, v68
	v_add_u32_e32 v130, 0x1200, v132
	v_add_u32_e32 v131, 0x1100, v134
	v_lshlrev_b32_e32 v0, 2, v108
	v_lshlrev_b32_e32 v136, 4, v108
	v_mul_u32_u24_e32 v135, 0x90, v118
	v_lshlrev_b64 v[80:81], 7, v[6:7]
	s_mov_b64 s[0:1], 0
	v_mov_b32_e32 v3, s36
	v_mov_b32_e32 v137, s6
	v_mov_b64_e32 v[6:7], s[30:31]

.LBB0_1035:
	s_lshl_b64 s[0:1], s[0:1], 2
	s_add_u32 s0, s46, s0
	s_addc_u32 s1, s47, s1
	s_lshr_b32 s3, s2, 7
	s_mul_i32 s36, s3, 0xc00
	s_ashr_i32 s37, s36, 31
	s_lshl_b64 s[36:37], s[36:37], 2
	s_add_u32 s3, s4, s36
	s_addc_u32 s34, s5, s37
	s_waitcnt vmcnt(0)
	v_lshrrev_b32_e32 v70, 3, v213
	v_and_b32_e32 v202, 31, v213
	s_lshl_b32 s38, s2, 6
	v_and_b32_e32 v71, 0xffffffc0, v213
	v_and_or_b32 v194, v70, 4, v71
	v_or_b32_e32 v72, s38, v202
	s_add_u32 s36, s3, 0x2100
	v_ashrrev_i32_e32 v195, 31, v194
	v_ashrrev_i32_e32 v73, 31, v72
	s_addc_u32 s37, s34, 0
	v_lshlrev_b64 v[108:109], 2, v[194:195]
	v_lshlrev_b64 v[72:73], 12, v[72:73]
	v_lshl_add_u64 v[70:71], s[36:37], 0, v[108:109]
	v_lshl_add_u64 v[76:77], v[68:69], 0, v[72:73]
	flat_load_dwordx4 v[214:217], v[70:71]
	flat_load_dwordx4 v[218:221], v[70:71] offset:32
	flat_load_dwordx4 v[222:225], v[70:71] offset:64
	flat_load_dwordx4 v[226:229], v[70:71] offset:96
	flat_load_dwordx4 v[230:233], v[70:71] offset:128
	flat_load_dwordx4 v[234:237], v[70:71] offset:160
	flat_load_dwordx4 v[238:241], v[70:71] offset:192
	flat_load_dwordx4 v[242:245], v[70:71] offset:224
	v_lshl_add_u64 v[196:197], v[76:77], 0, v[108:109]
	flat_load_dwordx4 v[76:79], v[196:197]
	v_lshlrev_b32_e32 v110, 12, v202
	v_lshl_add_u64 v[200:201], s[0:1], 0, v[108:109]
	v_lshl_add_u64 v[198:199], v[200:201], 0, v[110:111]
	flat_load_dwordx4 v[80:83], v[196:197] offset:32
	flat_load_dwordx4 v[84:87], v[196:197] offset:64
	flat_load_dwordx4 v[88:91], v[196:197] offset:96
	flat_load_dwordx4 v[92:95], v[196:197] offset:128
	flat_load_dwordx4 v[96:99], v[196:197] offset:160
	flat_load_dwordx4 v[100:103], v[196:197] offset:192
	flat_load_dwordx4 v[104:107], v[196:197] offset:224
	v_or_b32_e32 v195, 32, v202
	v_lshlrev_b32_e32 v110, 12, v195
	s_mov_b32 s3, 0
	s_waitcnt vmcnt(0) lgkmcnt(0)
	v_mov_b64_e32 v[72:73], v[214:215]
	v_mov_b64_e32 v[74:75], v[216:217]
	v_pk_mul_f32 v[48:49], v[48:49], v[72:73]
	v_pk_mul_f32 v[50:51], v[50:51], v[74:75]
	v_pk_fma_f32 v[48:49], v[76:77], s[26:27], v[48:49] op_sel_hi:[1,0,1]
	v_pk_fma_f32 v[50:51], v[78:79], s[26:27], v[50:51] op_sel_hi:[1,0,1]
	flat_store_dwordx4 v[198:199], v[48:51]
	s_nop 1
	v_mov_b64_e32 v[48:49], v[218:219]
	v_mov_b64_e32 v[50:51], v[220:221]
	v_lshl_add_u64 v[76:77], v[200:201], 0, v[110:111]
	v_lshlrev_b32_e32 v110, 10, v202
	v_lshlrev_b32_e32 v200, 10, v195
	v_mov_b64_e32 v[202:203], v[178:179]
	v_pk_mul_f32 v[48:49], v[52:53], v[48:49]
	v_pk_mul_f32 v[50:51], v[54:55], v[50:51]
	v_pk_fma_f32 v[48:49], v[80:81], s[26:27], v[48:49] op_sel_hi:[1,0,1]
	v_pk_fma_f32 v[50:51], v[82:83], s[26:27], v[50:51] op_sel_hi:[1,0,1]
	flat_store_dwordx4 v[198:199], v[48:51] offset:32
	s_nop 1
	v_mov_b64_e32 v[48:49], v[222:223]
	v_mov_b64_e32 v[50:51], v[224:225]
	v_pk_mul_f32 v[48:49], v[56:57], v[48:49]
	v_pk_mul_f32 v[50:51], v[58:59], v[50:51]
	v_pk_fma_f32 v[48:49], v[84:85], s[26:27], v[48:49] op_sel_hi:[1,0,1]
	v_pk_fma_f32 v[50:51], v[86:87], s[26:27], v[50:51] op_sel_hi:[1,0,1]
	flat_store_dwordx4 v[198:199], v[48:51] offset:64
	s_nop 1
	v_mov_b64_e32 v[48:49], v[226:227]
	v_mov_b64_e32 v[50:51], v[228:229]
	v_pk_mul_f32 v[48:49], v[60:61], v[48:49]
	v_pk_mul_f32 v[50:51], v[62:63], v[50:51]
	v_pk_fma_f32 v[48:49], v[88:89], s[26:27], v[48:49] op_sel_hi:[1,0,1]
	v_pk_fma_f32 v[50:51], v[90:91], s[26:27], v[50:51] op_sel_hi:[1,0,1]
	flat_store_dwordx4 v[198:199], v[48:51] offset:96
	s_nop 1
	v_mov_b64_e32 v[48:49], v[230:231]
	v_mov_b64_e32 v[50:51], v[232:233]
	v_pk_mul_f32 v[32:33], v[32:33], v[48:49]
	v_pk_mul_f32 v[34:35], v[34:35], v[50:51]
	v_pk_fma_f32 v[32:33], v[92:93], s[26:27], v[32:33] op_sel_hi:[1,0,1]
	v_pk_fma_f32 v[34:35], v[94:95], s[26:27], v[34:35] op_sel_hi:[1,0,1]
	flat_store_dwordx4 v[198:199], v[32:35] offset:128
	s_nop 1
	v_mov_b64_e32 v[32:33], v[234:235]
	v_mov_b64_e32 v[34:35], v[236:237]
	v_pk_mul_f32 v[32:33], v[36:37], v[32:33]
	v_pk_mul_f32 v[34:35], v[38:39], v[34:35]
	v_pk_fma_f32 v[32:33], v[96:97], s[26:27], v[32:33] op_sel_hi:[1,0,1]
	v_pk_fma_f32 v[34:35], v[98:99], s[26:27], v[34:35] op_sel_hi:[1,0,1]
	flat_store_dwordx4 v[198:199], v[32:35] offset:160
	s_nop 1
	v_mov_b64_e32 v[32:33], v[238:239]
	v_mov_b64_e32 v[34:35], v[240:241]
	v_or_b32_e32 v36, s38, v195
	v_ashrrev_i32_e32 v37, 31, v36
	v_lshlrev_b64 v[36:37], 12, v[36:37]
	v_lshl_add_u64 v[36:37], v[68:69], 0, v[36:37]
	v_pk_mul_f32 v[32:33], v[40:41], v[32:33]
	v_pk_mul_f32 v[34:35], v[42:43], v[34:35]
	v_pk_fma_f32 v[32:33], v[100:101], s[26:27], v[32:33] op_sel_hi:[1,0,1]
	v_pk_fma_f32 v[34:35], v[102:103], s[26:27], v[34:35] op_sel_hi:[1,0,1]
	flat_store_dwordx4 v[198:199], v[32:35] offset:192
	s_nop 1
	v_mov_b64_e32 v[32:33], v[242:243]
	v_mov_b64_e32 v[34:35], v[244:245]
	v_pk_mul_f32 v[32:33], v[44:45], v[32:33]
	v_pk_mul_f32 v[34:35], v[46:47], v[34:35]
	v_pk_fma_f32 v[32:33], v[104:105], s[26:27], v[32:33] op_sel_hi:[1,0,1]
	v_pk_fma_f32 v[34:35], v[106:107], s[26:27], v[34:35] op_sel_hi:[1,0,1]
	flat_store_dwordx4 v[198:199], v[32:35] offset:224
	s_nop 1
	v_mov_b64_e32 v[32:33], v[214:215]
	v_mov_b64_e32 v[34:35], v[216:217]
	v_lshl_add_u64 v[198:199], v[36:37], 0, v[108:109]
	flat_load_dwordx4 v[36:39], v[198:199]
	flat_load_dwordx4 v[40:43], v[198:199] offset:32
	flat_load_dwordx4 v[44:47], v[198:199] offset:64
	flat_load_dwordx4 v[48:51], v[198:199] offset:96
	flat_load_dwordx4 v[52:55], v[198:199] offset:128
	flat_load_dwordx4 v[56:59], v[198:199] offset:160
	flat_load_dwordx4 v[60:63], v[198:199] offset:192
	flat_load_dwordx4 v[72:75], v[198:199] offset:224
	s_waitcnt vmcnt(0) lgkmcnt(0)
	v_pk_mul_f32 v[16:17], v[16:17], v[32:33]
	v_pk_mul_f32 v[18:19], v[18:19], v[34:35]
	v_pk_fma_f32 v[16:17], v[36:37], s[26:27], v[16:17] op_sel_hi:[1,0,1]
	v_pk_fma_f32 v[18:19], v[38:39], s[26:27], v[18:19] op_sel_hi:[1,0,1]
	flat_store_dwordx4 v[76:77], v[16:19]
	s_nop 1
	v_mov_b64_e32 v[16:17], v[218:219]
	v_mov_b64_e32 v[18:19], v[220:221]
	v_pk_mul_f32 v[16:17], v[20:21], v[16:17]
	v_pk_mul_f32 v[18:19], v[22:23], v[18:19]
	v_pk_fma_f32 v[16:17], v[40:41], s[26:27], v[16:17] op_sel_hi:[1,0,1]
	v_pk_fma_f32 v[18:19], v[42:43], s[26:27], v[18:19] op_sel_hi:[1,0,1]
	flat_store_dwordx4 v[76:77], v[16:19] offset:32
	s_nop 1
	v_mov_b64_e32 v[16:17], v[222:223]
	v_mov_b64_e32 v[18:19], v[224:225]
	v_pk_mul_f32 v[16:17], v[24:25], v[16:17]
	v_pk_mul_f32 v[18:19], v[26:27], v[18:19]
	v_pk_fma_f32 v[16:17], v[44:45], s[26:27], v[16:17] op_sel_hi:[1,0,1]
	v_pk_fma_f32 v[18:19], v[46:47], s[26:27], v[18:19] op_sel_hi:[1,0,1]
	flat_store_dwordx4 v[76:77], v[16:19] offset:64
	s_nop 1
	v_mov_b64_e32 v[16:17], v[226:227]
	v_mov_b64_e32 v[18:19], v[228:229]
	v_pk_mul_f32 v[16:17], v[28:29], v[16:17]
	v_pk_mul_f32 v[18:19], v[30:31], v[18:19]
	v_pk_fma_f32 v[16:17], v[48:49], s[26:27], v[16:17] op_sel_hi:[1,0,1]
	v_pk_fma_f32 v[18:19], v[50:51], s[26:27], v[18:19] op_sel_hi:[1,0,1]
	flat_store_dwordx4 v[76:77], v[16:19] offset:96
	s_nop 1
	v_mov_b64_e32 v[16:17], v[230:231]
	v_mov_b64_e32 v[18:19], v[232:233]
	v_pk_mul_f32 v[0:1], v[0:1], v[16:17]
	v_pk_mul_f32 v[2:3], v[2:3], v[18:19]
	v_pk_fma_f32 v[0:1], v[52:53], s[26:27], v[0:1] op_sel_hi:[1,0,1]
	v_pk_fma_f32 v[2:3], v[54:55], s[26:27], v[2:3] op_sel_hi:[1,0,1]
	flat_store_dwordx4 v[76:77], v[0:3] offset:128
	s_nop 1
	v_mov_b64_e32 v[0:1], v[234:235]
	v_mov_b64_e32 v[2:3], v[236:237]
	v_pk_mul_f32 v[0:1], v[4:5], v[0:1]
	v_pk_mul_f32 v[2:3], v[6:7], v[2:3]
	v_pk_fma_f32 v[0:1], v[56:57], s[26:27], v[0:1] op_sel_hi:[1,0,1]
	v_pk_fma_f32 v[2:3], v[58:59], s[26:27], v[2:3] op_sel_hi:[1,0,1]
	flat_store_dwordx4 v[76:77], v[0:3] offset:160
	s_nop 1
	v_mov_b64_e32 v[0:1], v[238:239]
	v_mov_b64_e32 v[2:3], v[240:241]
	v_pk_mul_f32 v[0:1], v[8:9], v[0:1]
	v_pk_mul_f32 v[2:3], v[10:11], v[2:3]
	v_pk_fma_f32 v[0:1], v[60:61], s[26:27], v[0:1] op_sel_hi:[1,0,1]
	v_pk_fma_f32 v[2:3], v[62:63], s[26:27], v[2:3] op_sel_hi:[1,0,1]
	flat_store_dwordx4 v[76:77], v[0:3] offset:192
	s_nop 1
	v_mov_b64_e32 v[0:1], v[242:243]
	v_mov_b64_e32 v[2:3], v[244:245]
	v_pk_mul_f32 v[0:1], v[12:13], v[0:1]
	v_pk_mul_f32 v[2:3], v[14:15], v[2:3]
	v_pk_fma_f32 v[0:1], v[72:73], s[26:27], v[0:1] op_sel_hi:[1,0,1]
	v_pk_fma_f32 v[2:3], v[74:75], s[26:27], v[2:3] op_sel_hi:[1,0,1]
	flat_store_dwordx4 v[76:77], v[0:3] offset:224
	flat_load_dwordx4 v[70:73], v[190:191]
	s_nop 0
	flat_load_dwordx4 v[74:77], v[192:193]
	flat_load_dwordx4 v[98:101], v[128:129]
	flat_load_dwordx4 v[78:81], v[130:131]
	flat_load_dwordx4 v[82:85], v[132:133]
	flat_load_dwordx4 v[86:89], v[134:135]
	flat_load_dwordx4 v[90:93], v[136:137]
	flat_load_dwordx4 v[94:97], v[138:139]
	flat_load_dwordx4 v[102:105], v[140:141]
	flat_load_dwordx4 v[106:109], v[142:143]
	v_mov_b32_e32 v0, 0
	v_mov_b32_e32 v1, v0
	v_mov_b32_e32 v2, v0
	v_mov_b32_e32 v3, v0
	v_mov_b32_e32 v4, v0
	v_mov_b32_e32 v5, v0
	v_mov_b32_e32 v6, v0
	v_mov_b32_e32 v7, v0
	v_mov_b32_e32 v8, v0
	v_mov_b32_e32 v9, v0
	v_mov_b32_e32 v10, v0
	v_mov_b32_e32 v11, v0
	v_mov_b32_e32 v12, v0
	v_mov_b32_e32 v13, v0
	v_mov_b32_e32 v14, v0
	v_mov_b32_e32 v15, v0
	v_mov_b32_e32 v16, v0
	v_mov_b32_e32 v17, v0
	v_mov_b32_e32 v18, v0
	v_mov_b32_e32 v19, v0
	v_mov_b32_e32 v20, v0
	v_mov_b32_e32 v21, v0
	v_mov_b32_e32 v22, v0
	v_mov_b32_e32 v23, v0
	v_mov_b32_e32 v24, v0
	v_mov_b32_e32 v25, v0
	v_mov_b32_e32 v26, v0
	v_mov_b32_e32 v27, v0
	v_mov_b32_e32 v28, v0
	v_mov_b32_e32 v29, v0
	v_mov_b32_e32 v30, v0
	v_mov_b32_e32 v31, v0
	v_mov_b32_e32 v32, v0
	v_mov_b32_e32 v33, v0
	v_mov_b32_e32 v34, v0
	v_mov_b32_e32 v35, v0
	v_mov_b32_e32 v36, v0
	v_mov_b32_e32 v37, v0
	v_mov_b32_e32 v38, v0
	v_mov_b32_e32 v39, v0
	v_mov_b32_e32 v40, v0
	v_mov_b32_e32 v41, v0
	v_mov_b32_e32 v42, v0
	v_mov_b32_e32 v43, v0
	v_mov_b32_e32 v44, v0
	v_mov_b32_e32 v45, v0
	v_mov_b32_e32 v46, v0
	v_mov_b32_e32 v47, v0
	v_mov_b32_e32 v48, v0
	v_mov_b32_e32 v49, v0
	v_mov_b32_e32 v50, v0
	v_mov_b32_e32 v51, v0
	v_mov_b32_e32 v52, v0
	v_mov_b32_e32 v53, v0
	v_mov_b32_e32 v54, v0
	v_mov_b32_e32 v55, v0
	v_mov_b32_e32 v56, v0
	v_mov_b32_e32 v57, v0
	v_mov_b32_e32 v58, v0
	v_mov_b32_e32 v59, v0
	v_mov_b32_e32 v60, v0
	v_mov_b32_e32 v61, v0
	v_mov_b32_e32 v62, v0
	v_mov_b32_e32 v63, v0
	s_branch .LBB0_1037

.LBB0_1039:
	s_waitcnt vmcnt(0)
	v_add_u32_e32 v70, 0x100, v194
	v_ashrrev_i32_e32 v71, 31, v70
	v_lshlrev_b64 v[108:109], 2, v[70:71]
	v_lshl_add_u64 v[70:71], s[36:37], 0, v[108:109]
	flat_load_dwordx4 v[214:217], v[70:71]
	flat_load_dwordx4 v[218:221], v[70:71] offset:32
	flat_load_dwordx4 v[222:225], v[70:71] offset:64
	flat_load_dwordx4 v[226:229], v[70:71] offset:96
	flat_load_dwordx4 v[230:233], v[70:71] offset:128
	flat_load_dwordx4 v[234:237], v[70:71] offset:160
	flat_load_dwordx4 v[238:241], v[70:71] offset:192
	flat_load_dwordx4 v[242:245], v[70:71] offset:224
	flat_load_dwordx4 v[76:79], v[196:197] offset:1024
	flat_load_dwordx4 v[80:83], v[196:197] offset:1056
	flat_load_dwordx4 v[84:87], v[196:197] offset:1088
	flat_load_dwordx4 v[88:91], v[196:197] offset:1120
	flat_load_dwordx4 v[92:95], v[196:197] offset:1152
	flat_load_dwordx4 v[96:99], v[196:197] offset:1184
	flat_load_dwordx4 v[100:103], v[196:197] offset:1216
	flat_load_dwordx4 v[104:107], v[196:197] offset:1248
	v_lshlrev_b32_e32 v110, 2, v110
	v_lshl_add_u64 v[108:109], s[0:1], 0, v[108:109]
	v_lshl_add_u64 v[202:203], v[108:109], 0, v[110:111]
	v_lshlrev_b32_e32 v200, 2, v200
	v_mov_b32_e32 v201, v111
	s_mov_b32 s3, 0
	s_waitcnt vmcnt(0) lgkmcnt(0)
	v_mov_b64_e32 v[72:73], v[214:215]
	v_mov_b64_e32 v[74:75], v[216:217]
	v_pk_mul_f32 v[48:49], v[48:49], v[72:73]
	v_pk_mul_f32 v[50:51], v[50:51], v[74:75]
	v_pk_fma_f32 v[48:49], v[76:77], s[26:27], v[48:49] op_sel_hi:[1,0,1]
	v_pk_fma_f32 v[50:51], v[78:79], s[26:27], v[50:51] op_sel_hi:[1,0,1]
	flat_store_dwordx4 v[202:203], v[48:51]
	s_nop 1
	v_mov_b64_e32 v[48:49], v[218:219]
	v_mov_b64_e32 v[50:51], v[220:221]
	v_lshl_add_u64 v[76:77], v[108:109], 0, v[200:201]
	v_pk_mul_f32 v[48:49], v[52:53], v[48:49]
	v_pk_mul_f32 v[50:51], v[54:55], v[50:51]
	v_pk_fma_f32 v[48:49], v[80:81], s[26:27], v[48:49] op_sel_hi:[1,0,1]
	v_pk_fma_f32 v[50:51], v[82:83], s[26:27], v[50:51] op_sel_hi:[1,0,1]
	flat_store_dwordx4 v[202:203], v[48:51] offset:32
	s_nop 1
	v_mov_b64_e32 v[48:49], v[222:223]
	v_mov_b64_e32 v[50:51], v[224:225]
	v_pk_mul_f32 v[48:49], v[56:57], v[48:49]
	v_pk_mul_f32 v[50:51], v[58:59], v[50:51]
	v_pk_fma_f32 v[48:49], v[84:85], s[26:27], v[48:49] op_sel_hi:[1,0,1]
	v_pk_fma_f32 v[50:51], v[86:87], s[26:27], v[50:51] op_sel_hi:[1,0,1]
	flat_store_dwordx4 v[202:203], v[48:51] offset:64
	s_nop 1
	v_mov_b64_e32 v[48:49], v[226:227]
	v_mov_b64_e32 v[50:51], v[228:229]
	v_pk_mul_f32 v[48:49], v[60:61], v[48:49]
	v_pk_mul_f32 v[50:51], v[62:63], v[50:51]
	v_pk_fma_f32 v[48:49], v[88:89], s[26:27], v[48:49] op_sel_hi:[1,0,1]
	v_pk_fma_f32 v[50:51], v[90:91], s[26:27], v[50:51] op_sel_hi:[1,0,1]
	flat_store_dwordx4 v[202:203], v[48:51] offset:96
	s_nop 1
	v_mov_b64_e32 v[48:49], v[230:231]
	v_mov_b64_e32 v[50:51], v[232:233]
	v_pk_mul_f32 v[32:33], v[32:33], v[48:49]
	v_pk_mul_f32 v[34:35], v[34:35], v[50:51]
	v_pk_fma_f32 v[32:33], v[92:93], s[26:27], v[32:33] op_sel_hi:[1,0,1]
	v_pk_fma_f32 v[34:35], v[94:95], s[26:27], v[34:35] op_sel_hi:[1,0,1]
	flat_store_dwordx4 v[202:203], v[32:35] offset:128
	s_nop 1
	v_mov_b64_e32 v[32:33], v[234:235]
	v_mov_b64_e32 v[34:35], v[236:237]
	v_pk_mul_f32 v[32:33], v[36:37], v[32:33]
	v_pk_mul_f32 v[34:35], v[38:39], v[34:35]
	v_pk_fma_f32 v[32:33], v[96:97], s[26:27], v[32:33] op_sel_hi:[1,0,1]
	v_pk_fma_f32 v[34:35], v[98:99], s[26:27], v[34:35] op_sel_hi:[1,0,1]
	flat_store_dwordx4 v[202:203], v[32:35] offset:160
	s_nop 1
	v_mov_b64_e32 v[32:33], v[238:239]
	v_mov_b64_e32 v[34:35], v[240:241]
	v_pk_mul_f32 v[32:33], v[40:41], v[32:33]
	v_pk_mul_f32 v[34:35], v[42:43], v[34:35]
	v_pk_fma_f32 v[32:33], v[100:101], s[26:27], v[32:33] op_sel_hi:[1,0,1]
	v_pk_fma_f32 v[34:35], v[102:103], s[26:27], v[34:35] op_sel_hi:[1,0,1]
	flat_store_dwordx4 v[202:203], v[32:35] offset:192
	s_nop 1
	v_mov_b64_e32 v[32:33], v[242:243]
	v_mov_b64_e32 v[34:35], v[244:245]
	v_pk_mul_f32 v[32:33], v[44:45], v[32:33]
	v_pk_mul_f32 v[34:35], v[46:47], v[34:35]
	v_pk_fma_f32 v[32:33], v[104:105], s[26:27], v[32:33] op_sel_hi:[1,0,1]
	v_pk_fma_f32 v[34:35], v[106:107], s[26:27], v[34:35] op_sel_hi:[1,0,1]
	flat_store_dwordx4 v[202:203], v[32:35] offset:224
	s_nop 1
	v_mov_b64_e32 v[32:33], v[214:215]
	v_mov_b64_e32 v[34:35], v[216:217]
	s_nop 0
	flat_load_dwordx4 v[36:39], v[198:199] offset:1024
	flat_load_dwordx4 v[40:43], v[198:199] offset:1056
	flat_load_dwordx4 v[44:47], v[198:199] offset:1088
	flat_load_dwordx4 v[48:51], v[198:199] offset:1120
	flat_load_dwordx4 v[52:55], v[198:199] offset:1152
	flat_load_dwordx4 v[56:59], v[198:199] offset:1184
	flat_load_dwordx4 v[60:63], v[198:199] offset:1216
	flat_load_dwordx4 v[72:75], v[198:199] offset:1248
	v_mov_b64_e32 v[202:203], v[180:181]
	s_waitcnt vmcnt(0) lgkmcnt(0)
	v_pk_mul_f32 v[16:17], v[16:17], v[32:33]
	v_pk_mul_f32 v[18:19], v[18:19], v[34:35]
	v_pk_fma_f32 v[16:17], v[36:37], s[26:27], v[16:17] op_sel_hi:[1,0,1]
	v_pk_fma_f32 v[18:19], v[38:39], s[26:27], v[18:19] op_sel_hi:[1,0,1]
	flat_store_dwordx4 v[76:77], v[16:19]
	s_nop 1
	v_mov_b64_e32 v[16:17], v[218:219]
	v_mov_b64_e32 v[18:19], v[220:221]
	v_pk_mul_f32 v[16:17], v[20:21], v[16:17]
	v_pk_mul_f32 v[18:19], v[22:23], v[18:19]
	v_pk_fma_f32 v[16:17], v[40:41], s[26:27], v[16:17] op_sel_hi:[1,0,1]
	v_pk_fma_f32 v[18:19], v[42:43], s[26:27], v[18:19] op_sel_hi:[1,0,1]
	flat_store_dwordx4 v[76:77], v[16:19] offset:32
	s_nop 1
	v_mov_b64_e32 v[16:17], v[222:223]
	v_mov_b64_e32 v[18:19], v[224:225]
	v_pk_mul_f32 v[16:17], v[24:25], v[16:17]
	v_pk_mul_f32 v[18:19], v[26:27], v[18:19]
	v_pk_fma_f32 v[16:17], v[44:45], s[26:27], v[16:17] op_sel_hi:[1,0,1]
	v_pk_fma_f32 v[18:19], v[46:47], s[26:27], v[18:19] op_sel_hi:[1,0,1]
	flat_store_dwordx4 v[76:77], v[16:19] offset:64
	s_nop 1
	v_mov_b64_e32 v[16:17], v[226:227]
	v_mov_b64_e32 v[18:19], v[228:229]
	v_pk_mul_f32 v[16:17], v[28:29], v[16:17]
	v_pk_mul_f32 v[18:19], v[30:31], v[18:19]
	v_pk_fma_f32 v[16:17], v[48:49], s[26:27], v[16:17] op_sel_hi:[1,0,1]
	v_pk_fma_f32 v[18:19], v[50:51], s[26:27], v[18:19] op_sel_hi:[1,0,1]
	flat_store_dwordx4 v[76:77], v[16:19] offset:96
	s_nop 1
	v_mov_b64_e32 v[16:17], v[230:231]
	v_mov_b64_e32 v[18:19], v[232:233]
	v_pk_mul_f32 v[0:1], v[0:1], v[16:17]
	v_pk_mul_f32 v[2:3], v[2:3], v[18:19]
	v_pk_fma_f32 v[0:1], v[52:53], s[26:27], v[0:1] op_sel_hi:[1,0,1]
	v_pk_fma_f32 v[2:3], v[54:55], s[26:27], v[2:3] op_sel_hi:[1,0,1]
	flat_store_dwordx4 v[76:77], v[0:3] offset:128
	s_nop 1
	v_mov_b64_e32 v[0:1], v[234:235]
	v_mov_b64_e32 v[2:3], v[236:237]
	v_pk_mul_f32 v[0:1], v[4:5], v[0:1]
	v_pk_mul_f32 v[2:3], v[6:7], v[2:3]
	v_pk_fma_f32 v[0:1], v[56:57], s[26:27], v[0:1] op_sel_hi:[1,0,1]
	v_pk_fma_f32 v[2:3], v[58:59], s[26:27], v[2:3] op_sel_hi:[1,0,1]
	flat_store_dwordx4 v[76:77], v[0:3] offset:160
	s_nop 1
	v_mov_b64_e32 v[0:1], v[238:239]
	v_mov_b64_e32 v[2:3], v[240:241]
	v_pk_mul_f32 v[0:1], v[8:9], v[0:1]
	v_pk_mul_f32 v[2:3], v[10:11], v[2:3]
	v_pk_fma_f32 v[0:1], v[60:61], s[26:27], v[0:1] op_sel_hi:[1,0,1]
	v_pk_fma_f32 v[2:3], v[62:63], s[26:27], v[2:3] op_sel_hi:[1,0,1]
	flat_store_dwordx4 v[76:77], v[0:3] offset:192
	s_nop 1
	v_mov_b64_e32 v[0:1], v[242:243]
	v_mov_b64_e32 v[2:3], v[244:245]
	v_pk_mul_f32 v[0:1], v[12:13], v[0:1]
	v_pk_mul_f32 v[2:3], v[14:15], v[2:3]
	v_pk_fma_f32 v[0:1], v[72:73], s[26:27], v[0:1] op_sel_hi:[1,0,1]
	v_pk_fma_f32 v[2:3], v[74:75], s[26:27], v[2:3] op_sel_hi:[1,0,1]
	flat_store_dwordx4 v[76:77], v[0:3] offset:224
	flat_load_dwordx4 v[70:73], v[190:191]
	s_nop 0
	flat_load_dwordx4 v[74:77], v[192:193]
	flat_load_dwordx4 v[98:101], v[144:145]
	flat_load_dwordx4 v[78:81], v[146:147]
	flat_load_dwordx4 v[82:85], v[148:149]
	flat_load_dwordx4 v[86:89], v[150:151]
	flat_load_dwordx4 v[90:93], v[152:153]
	flat_load_dwordx4 v[94:97], v[154:155]
	flat_load_dwordx4 v[102:105], v[156:157]
	flat_load_dwordx4 v[106:109], v[158:159]
	v_mov_b32_e32 v0, 0
	v_mov_b32_e32 v1, v0
	v_mov_b32_e32 v2, v0
	v_mov_b32_e32 v3, v0
	v_mov_b32_e32 v4, v0
	v_mov_b32_e32 v5, v0
	v_mov_b32_e32 v6, v0
	v_mov_b32_e32 v7, v0
	v_mov_b32_e32 v8, v0
	v_mov_b32_e32 v9, v0
	v_mov_b32_e32 v10, v0
	v_mov_b32_e32 v11, v0
	v_mov_b32_e32 v12, v0
	v_mov_b32_e32 v13, v0
	v_mov_b32_e32 v14, v0
	v_mov_b32_e32 v15, v0
	v_mov_b32_e32 v16, v0
	v_mov_b32_e32 v17, v0
	v_mov_b32_e32 v18, v0
	v_mov_b32_e32 v19, v0
	v_mov_b32_e32 v20, v0
	v_mov_b32_e32 v21, v0
	v_mov_b32_e32 v22, v0
	v_mov_b32_e32 v23, v0
	v_mov_b32_e32 v24, v0
	v_mov_b32_e32 v25, v0
	v_mov_b32_e32 v26, v0
	v_mov_b32_e32 v27, v0
	v_mov_b32_e32 v28, v0
	v_mov_b32_e32 v29, v0
	v_mov_b32_e32 v30, v0
	v_mov_b32_e32 v31, v0
	v_mov_b32_e32 v32, v0
	v_mov_b32_e32 v33, v0
	v_mov_b32_e32 v34, v0
	v_mov_b32_e32 v35, v0
	v_mov_b32_e32 v36, v0
	v_mov_b32_e32 v37, v0
	v_mov_b32_e32 v38, v0
	v_mov_b32_e32 v39, v0
	v_mov_b32_e32 v40, v0
	v_mov_b32_e32 v41, v0
	v_mov_b32_e32 v42, v0
	v_mov_b32_e32 v43, v0
	v_mov_b32_e32 v44, v0
	v_mov_b32_e32 v45, v0
	v_mov_b32_e32 v46, v0
	v_mov_b32_e32 v47, v0
	v_mov_b32_e32 v48, v0
	v_mov_b32_e32 v49, v0
	v_mov_b32_e32 v50, v0
	v_mov_b32_e32 v51, v0
	v_mov_b32_e32 v52, v0
	v_mov_b32_e32 v53, v0
	v_mov_b32_e32 v54, v0
	v_mov_b32_e32 v55, v0
	v_mov_b32_e32 v56, v0
	v_mov_b32_e32 v57, v0
	v_mov_b32_e32 v58, v0
	v_mov_b32_e32 v59, v0
	v_mov_b32_e32 v60, v0
	v_mov_b32_e32 v61, v0
	v_mov_b32_e32 v62, v0
	v_mov_b32_e32 v63, v0
	s_branch .LBB0_1041

.LBB0_1043:
	s_waitcnt vmcnt(0)
	v_add_u32_e32 v70, 0x200, v194
	v_ashrrev_i32_e32 v71, 31, v70
	v_lshlrev_b64 v[108:109], 2, v[70:71]
	v_lshl_add_u64 v[70:71], s[36:37], 0, v[108:109]
	flat_load_dwordx4 v[214:217], v[70:71]
	flat_load_dwordx4 v[218:221], v[70:71] offset:32
	flat_load_dwordx4 v[222:225], v[70:71] offset:64
	flat_load_dwordx4 v[226:229], v[70:71] offset:96
	flat_load_dwordx4 v[230:233], v[70:71] offset:128
	flat_load_dwordx4 v[234:237], v[70:71] offset:160
	flat_load_dwordx4 v[238:241], v[70:71] offset:192
	flat_load_dwordx4 v[242:245], v[70:71] offset:224
	flat_load_dwordx4 v[76:79], v[196:197] offset:2048
	flat_load_dwordx4 v[80:83], v[196:197] offset:2080
	flat_load_dwordx4 v[84:87], v[196:197] offset:2112
	flat_load_dwordx4 v[88:91], v[196:197] offset:2144
	flat_load_dwordx4 v[92:95], v[196:197] offset:2176
	flat_load_dwordx4 v[96:99], v[196:197] offset:2208
	flat_load_dwordx4 v[100:103], v[196:197] offset:2240
	flat_load_dwordx4 v[104:107], v[196:197] offset:2272
	v_lshl_add_u64 v[108:109], s[0:1], 0, v[108:109]
	v_lshl_add_u64 v[202:203], v[108:109], 0, v[110:111]
	v_mov_b32_e32 v201, v111
	s_mov_b32 s3, 0
	s_waitcnt vmcnt(0) lgkmcnt(0)
	v_mov_b64_e32 v[72:73], v[214:215]
	v_mov_b64_e32 v[74:75], v[216:217]
	v_pk_mul_f32 v[48:49], v[48:49], v[72:73]
	v_pk_mul_f32 v[50:51], v[50:51], v[74:75]
	v_pk_fma_f32 v[48:49], v[76:77], s[26:27], v[48:49] op_sel_hi:[1,0,1]
	v_pk_fma_f32 v[50:51], v[78:79], s[26:27], v[50:51] op_sel_hi:[1,0,1]
	flat_store_dwordx4 v[202:203], v[48:51]
	s_nop 1
	v_mov_b64_e32 v[48:49], v[218:219]
	v_mov_b64_e32 v[50:51], v[220:221]
	v_lshl_add_u64 v[76:77], v[108:109], 0, v[200:201]
	v_pk_mul_f32 v[48:49], v[52:53], v[48:49]
	v_pk_mul_f32 v[50:51], v[54:55], v[50:51]
	v_pk_fma_f32 v[48:49], v[80:81], s[26:27], v[48:49] op_sel_hi:[1,0,1]
	v_pk_fma_f32 v[50:51], v[82:83], s[26:27], v[50:51] op_sel_hi:[1,0,1]
	flat_store_dwordx4 v[202:203], v[48:51] offset:32
	s_nop 1
	v_mov_b64_e32 v[48:49], v[222:223]
	v_mov_b64_e32 v[50:51], v[224:225]
	v_pk_mul_f32 v[48:49], v[56:57], v[48:49]
	v_pk_mul_f32 v[50:51], v[58:59], v[50:51]
	v_pk_fma_f32 v[48:49], v[84:85], s[26:27], v[48:49] op_sel_hi:[1,0,1]
	v_pk_fma_f32 v[50:51], v[86:87], s[26:27], v[50:51] op_sel_hi:[1,0,1]
	flat_store_dwordx4 v[202:203], v[48:51] offset:64
	s_nop 1
	v_mov_b64_e32 v[48:49], v[226:227]
	v_mov_b64_e32 v[50:51], v[228:229]
	v_pk_mul_f32 v[48:49], v[60:61], v[48:49]
	v_pk_mul_f32 v[50:51], v[62:63], v[50:51]
	v_pk_fma_f32 v[48:49], v[88:89], s[26:27], v[48:49] op_sel_hi:[1,0,1]
	v_pk_fma_f32 v[50:51], v[90:91], s[26:27], v[50:51] op_sel_hi:[1,0,1]
	flat_store_dwordx4 v[202:203], v[48:51] offset:96
	s_nop 1
	v_mov_b64_e32 v[48:49], v[230:231]
	v_mov_b64_e32 v[50:51], v[232:233]
	v_pk_mul_f32 v[32:33], v[32:33], v[48:49]
	v_pk_mul_f32 v[34:35], v[34:35], v[50:51]
	v_pk_fma_f32 v[32:33], v[92:93], s[26:27], v[32:33] op_sel_hi:[1,0,1]
	v_pk_fma_f32 v[34:35], v[94:95], s[26:27], v[34:35] op_sel_hi:[1,0,1]
	flat_store_dwordx4 v[202:203], v[32:35] offset:128
	s_nop 1
	v_mov_b64_e32 v[32:33], v[234:235]
	v_mov_b64_e32 v[34:35], v[236:237]
	v_pk_mul_f32 v[32:33], v[36:37], v[32:33]
	v_pk_mul_f32 v[34:35], v[38:39], v[34:35]
	v_pk_fma_f32 v[32:33], v[96:97], s[26:27], v[32:33] op_sel_hi:[1,0,1]
	v_pk_fma_f32 v[34:35], v[98:99], s[26:27], v[34:35] op_sel_hi:[1,0,1]
	flat_store_dwordx4 v[202:203], v[32:35] offset:160
	s_nop 1
	v_mov_b64_e32 v[32:33], v[238:239]
	v_mov_b64_e32 v[34:35], v[240:241]
	v_pk_mul_f32 v[32:33], v[40:41], v[32:33]
	v_pk_mul_f32 v[34:35], v[42:43], v[34:35]
	v_pk_fma_f32 v[32:33], v[100:101], s[26:27], v[32:33] op_sel_hi:[1,0,1]
	v_pk_fma_f32 v[34:35], v[102:103], s[26:27], v[34:35] op_sel_hi:[1,0,1]
	flat_store_dwordx4 v[202:203], v[32:35] offset:192
	s_nop 1
	v_mov_b64_e32 v[32:33], v[242:243]
	v_mov_b64_e32 v[34:35], v[244:245]
	v_pk_mul_f32 v[32:33], v[44:45], v[32:33]
	v_pk_mul_f32 v[34:35], v[46:47], v[34:35]
	v_pk_fma_f32 v[32:33], v[104:105], s[26:27], v[32:33] op_sel_hi:[1,0,1]
	v_pk_fma_f32 v[34:35], v[106:107], s[26:27], v[34:35] op_sel_hi:[1,0,1]
	flat_store_dwordx4 v[202:203], v[32:35] offset:224
	s_nop 1
	v_mov_b64_e32 v[32:33], v[214:215]
	v_mov_b64_e32 v[34:35], v[216:217]
	s_nop 0
	flat_load_dwordx4 v[36:39], v[198:199] offset:2048
	flat_load_dwordx4 v[40:43], v[198:199] offset:2080
	flat_load_dwordx4 v[44:47], v[198:199] offset:2112
	flat_load_dwordx4 v[48:51], v[198:199] offset:2144
	flat_load_dwordx4 v[52:55], v[198:199] offset:2176
	flat_load_dwordx4 v[56:59], v[198:199] offset:2208
	flat_load_dwordx4 v[60:63], v[198:199] offset:2240
	flat_load_dwordx4 v[72:75], v[198:199] offset:2272
	s_waitcnt vmcnt(0) lgkmcnt(0)
	v_pk_mul_f32 v[16:17], v[16:17], v[32:33]
	v_pk_mul_f32 v[18:19], v[18:19], v[34:35]
	v_pk_fma_f32 v[16:17], v[36:37], s[26:27], v[16:17] op_sel_hi:[1,0,1]
	v_pk_fma_f32 v[18:19], v[38:39], s[26:27], v[18:19] op_sel_hi:[1,0,1]
	flat_store_dwordx4 v[76:77], v[16:19]
	s_nop 1
	v_mov_b64_e32 v[16:17], v[218:219]
	v_mov_b64_e32 v[18:19], v[220:221]
	v_pk_mul_f32 v[16:17], v[20:21], v[16:17]
	v_pk_mul_f32 v[18:19], v[22:23], v[18:19]
	v_pk_fma_f32 v[16:17], v[40:41], s[26:27], v[16:17] op_sel_hi:[1,0,1]
	v_pk_fma_f32 v[18:19], v[42:43], s[26:27], v[18:19] op_sel_hi:[1,0,1]
	flat_store_dwordx4 v[76:77], v[16:19] offset:32
	s_nop 1
	v_mov_b64_e32 v[16:17], v[222:223]
	v_mov_b64_e32 v[18:19], v[224:225]
	v_pk_mul_f32 v[16:17], v[24:25], v[16:17]
	v_pk_mul_f32 v[18:19], v[26:27], v[18:19]
	v_pk_fma_f32 v[16:17], v[44:45], s[26:27], v[16:17] op_sel_hi:[1,0,1]
	v_pk_fma_f32 v[18:19], v[46:47], s[26:27], v[18:19] op_sel_hi:[1,0,1]
	flat_store_dwordx4 v[76:77], v[16:19] offset:64
	s_nop 1
	v_mov_b64_e32 v[16:17], v[226:227]
	v_mov_b64_e32 v[18:19], v[228:229]
	v_pk_mul_f32 v[16:17], v[28:29], v[16:17]
	v_pk_mul_f32 v[18:19], v[30:31], v[18:19]
	v_pk_fma_f32 v[16:17], v[48:49], s[26:27], v[16:17] op_sel_hi:[1,0,1]
	v_pk_fma_f32 v[18:19], v[50:51], s[26:27], v[18:19] op_sel_hi:[1,0,1]
	flat_store_dwordx4 v[76:77], v[16:19] offset:96
	s_nop 1
	v_mov_b64_e32 v[16:17], v[230:231]
	v_mov_b64_e32 v[18:19], v[232:233]
	v_pk_mul_f32 v[0:1], v[0:1], v[16:17]
	v_pk_mul_f32 v[2:3], v[2:3], v[18:19]
	v_pk_fma_f32 v[0:1], v[52:53], s[26:27], v[0:1] op_sel_hi:[1,0,1]
	v_pk_fma_f32 v[2:3], v[54:55], s[26:27], v[2:3] op_sel_hi:[1,0,1]
	flat_store_dwordx4 v[76:77], v[0:3] offset:128
	s_nop 1
	v_mov_b64_e32 v[0:1], v[234:235]
	v_mov_b64_e32 v[2:3], v[236:237]
	v_pk_mul_f32 v[0:1], v[4:5], v[0:1]
	v_pk_mul_f32 v[2:3], v[6:7], v[2:3]
	v_pk_fma_f32 v[0:1], v[56:57], s[26:27], v[0:1] op_sel_hi:[1,0,1]
	v_pk_fma_f32 v[2:3], v[58:59], s[26:27], v[2:3] op_sel_hi:[1,0,1]
	flat_store_dwordx4 v[76:77], v[0:3] offset:160
	s_nop 1
	v_mov_b64_e32 v[0:1], v[238:239]
	v_mov_b64_e32 v[2:3], v[240:241]
	v_pk_mul_f32 v[0:1], v[8:9], v[0:1]
	v_pk_mul_f32 v[2:3], v[10:11], v[2:3]
	v_pk_fma_f32 v[0:1], v[60:61], s[26:27], v[0:1] op_sel_hi:[1,0,1]
	v_pk_fma_f32 v[2:3], v[62:63], s[26:27], v[2:3] op_sel_hi:[1,0,1]
	flat_store_dwordx4 v[76:77], v[0:3] offset:192
	s_nop 1
	v_mov_b64_e32 v[0:1], v[242:243]
	v_mov_b64_e32 v[2:3], v[244:245]
	v_pk_mul_f32 v[0:1], v[12:13], v[0:1]
	v_pk_mul_f32 v[2:3], v[14:15], v[2:3]
	v_pk_fma_f32 v[0:1], v[72:73], s[26:27], v[0:1] op_sel_hi:[1,0,1]
	v_pk_fma_f32 v[2:3], v[74:75], s[26:27], v[2:3] op_sel_hi:[1,0,1]
	flat_store_dwordx4 v[76:77], v[0:3] offset:224
	flat_load_dwordx4 v[70:73], v[190:191]
	s_nop 0
	flat_load_dwordx4 v[74:77], v[192:193]
	flat_load_dwordx4 v[98:101], v[160:161]
	flat_load_dwordx4 v[78:81], v[162:163]
	flat_load_dwordx4 v[82:85], v[164:165]
	flat_load_dwordx4 v[86:89], v[166:167]
	flat_load_dwordx4 v[90:93], v[168:169]
	flat_load_dwordx4 v[94:97], v[170:171]
	flat_load_dwordx4 v[102:105], v[172:173]
	flat_load_dwordx4 v[106:109], v[174:175]
	v_mov_b32_e32 v0, 0
	v_mov_b64_e32 v[190:191], v[182:183]
	v_mov_b32_e32 v1, v0
	v_mov_b32_e32 v2, v0
	v_mov_b32_e32 v3, v0
	v_mov_b32_e32 v4, v0
	v_mov_b32_e32 v5, v0
	v_mov_b32_e32 v6, v0
	v_mov_b32_e32 v7, v0
	v_mov_b32_e32 v8, v0
	v_mov_b32_e32 v9, v0
	v_mov_b32_e32 v10, v0
	v_mov_b32_e32 v11, v0
	v_mov_b32_e32 v12, v0
	v_mov_b32_e32 v13, v0
	v_mov_b32_e32 v14, v0
	v_mov_b32_e32 v15, v0
	v_mov_b32_e32 v16, v0
	v_mov_b32_e32 v17, v0
	v_mov_b32_e32 v18, v0
	v_mov_b32_e32 v19, v0
	v_mov_b32_e32 v20, v0
	v_mov_b32_e32 v21, v0
	v_mov_b32_e32 v22, v0
	v_mov_b32_e32 v23, v0
	v_mov_b32_e32 v24, v0
	v_mov_b32_e32 v25, v0
	v_mov_b32_e32 v26, v0
	v_mov_b32_e32 v27, v0
	v_mov_b32_e32 v28, v0
	v_mov_b32_e32 v29, v0
	v_mov_b32_e32 v30, v0
	v_mov_b32_e32 v31, v0
	v_mov_b32_e32 v32, v0
	v_mov_b32_e32 v33, v0
	v_mov_b32_e32 v34, v0
	v_mov_b32_e32 v35, v0
	v_mov_b32_e32 v36, v0
	v_mov_b32_e32 v37, v0
	v_mov_b32_e32 v38, v0
	v_mov_b32_e32 v39, v0
	v_mov_b32_e32 v40, v0
	v_mov_b32_e32 v41, v0
	v_mov_b32_e32 v42, v0
	v_mov_b32_e32 v43, v0
	v_mov_b32_e32 v44, v0
	v_mov_b32_e32 v45, v0
	v_mov_b32_e32 v46, v0
	v_mov_b32_e32 v47, v0
	v_mov_b32_e32 v48, v0
	v_mov_b32_e32 v49, v0
	v_mov_b32_e32 v50, v0
	v_mov_b32_e32 v51, v0
	v_mov_b32_e32 v52, v0
	v_mov_b32_e32 v53, v0
	v_mov_b32_e32 v54, v0
	v_mov_b32_e32 v55, v0
	v_mov_b32_e32 v56, v0
	v_mov_b32_e32 v57, v0
	v_mov_b32_e32 v58, v0
	v_mov_b32_e32 v59, v0
	v_mov_b32_e32 v60, v0
	v_mov_b32_e32 v61, v0
	v_mov_b32_e32 v62, v0
	v_mov_b32_e32 v63, v0
	s_branch .LBB0_1045

.LBB0_1047:
	s_waitcnt vmcnt(0)
	v_add_u32_e32 v70, 0x300, v194
	v_ashrrev_i32_e32 v71, 31, v70
	v_lshlrev_b64 v[108:109], 2, v[70:71]
	v_lshl_add_u64 v[70:71], s[36:37], 0, v[108:109]
	flat_load_dwordx4 v[214:217], v[70:71]
	flat_load_dwordx4 v[218:221], v[70:71] offset:32
	flat_load_dwordx4 v[222:225], v[70:71] offset:64
	flat_load_dwordx4 v[226:229], v[70:71] offset:96
	flat_load_dwordx4 v[230:233], v[70:71] offset:128
	flat_load_dwordx4 v[234:237], v[70:71] offset:160
	flat_load_dwordx4 v[238:241], v[70:71] offset:192
	flat_load_dwordx4 v[242:245], v[70:71] offset:224
	flat_load_dwordx4 v[76:79], v[196:197] offset:3072
	flat_load_dwordx4 v[80:83], v[196:197] offset:3104
	flat_load_dwordx4 v[84:87], v[196:197] offset:3136
	flat_load_dwordx4 v[88:91], v[196:197] offset:3168
	flat_load_dwordx4 v[92:95], v[196:197] offset:3200
	flat_load_dwordx4 v[96:99], v[196:197] offset:3232
	flat_load_dwordx4 v[100:103], v[196:197] offset:3264
	flat_load_dwordx4 v[104:107], v[196:197] offset:3296
	v_lshl_add_u64 v[108:109], s[0:1], 0, v[108:109]
	v_lshl_add_u64 v[190:191], v[108:109], 0, v[110:111]
	v_mov_b32_e32 v201, v111
	s_mov_b32 s3, -2
	s_waitcnt vmcnt(0) lgkmcnt(0)
	v_mov_b64_e32 v[72:73], v[214:215]
	v_mov_b64_e32 v[74:75], v[216:217]
	v_pk_mul_f32 v[48:49], v[48:49], v[72:73]
	v_pk_mul_f32 v[50:51], v[50:51], v[74:75]
	v_pk_fma_f32 v[48:49], v[76:77], s[26:27], v[48:49] op_sel_hi:[1,0,1]
	v_pk_fma_f32 v[50:51], v[78:79], s[26:27], v[50:51] op_sel_hi:[1,0,1]
	flat_store_dwordx4 v[190:191], v[48:51]
	s_nop 1
	v_mov_b64_e32 v[48:49], v[218:219]
	v_mov_b64_e32 v[50:51], v[220:221]
	v_lshl_add_u64 v[76:77], v[108:109], 0, v[200:201]
	v_pk_mul_f32 v[48:49], v[52:53], v[48:49]
	v_pk_mul_f32 v[50:51], v[54:55], v[50:51]
	v_pk_fma_f32 v[48:49], v[80:81], s[26:27], v[48:49] op_sel_hi:[1,0,1]
	v_pk_fma_f32 v[50:51], v[82:83], s[26:27], v[50:51] op_sel_hi:[1,0,1]
	flat_store_dwordx4 v[190:191], v[48:51] offset:32
	s_nop 1
	v_mov_b64_e32 v[48:49], v[222:223]
	v_mov_b64_e32 v[50:51], v[224:225]
	v_pk_mul_f32 v[48:49], v[56:57], v[48:49]
	v_pk_mul_f32 v[50:51], v[58:59], v[50:51]
	v_pk_fma_f32 v[48:49], v[84:85], s[26:27], v[48:49] op_sel_hi:[1,0,1]
	v_pk_fma_f32 v[50:51], v[86:87], s[26:27], v[50:51] op_sel_hi:[1,0,1]
	flat_store_dwordx4 v[190:191], v[48:51] offset:64
	s_nop 1
	v_mov_b64_e32 v[48:49], v[226:227]
	v_mov_b64_e32 v[50:51], v[228:229]
	v_pk_mul_f32 v[48:49], v[60:61], v[48:49]
	v_pk_mul_f32 v[50:51], v[62:63], v[50:51]
	v_pk_fma_f32 v[48:49], v[88:89], s[26:27], v[48:49] op_sel_hi:[1,0,1]
	v_pk_fma_f32 v[50:51], v[90:91], s[26:27], v[50:51] op_sel_hi:[1,0,1]
	flat_store_dwordx4 v[190:191], v[48:51] offset:96
	s_nop 1
	v_mov_b64_e32 v[48:49], v[230:231]
	v_mov_b64_e32 v[50:51], v[232:233]
	v_pk_mul_f32 v[32:33], v[32:33], v[48:49]
	v_pk_mul_f32 v[34:35], v[34:35], v[50:51]
	v_pk_fma_f32 v[32:33], v[92:93], s[26:27], v[32:33] op_sel_hi:[1,0,1]
	v_pk_fma_f32 v[34:35], v[94:95], s[26:27], v[34:35] op_sel_hi:[1,0,1]
	flat_store_dwordx4 v[190:191], v[32:35] offset:128
	s_nop 1
	v_mov_b64_e32 v[32:33], v[234:235]
	v_mov_b64_e32 v[34:35], v[236:237]
	v_pk_mul_f32 v[32:33], v[36:37], v[32:33]
	v_pk_mul_f32 v[34:35], v[38:39], v[34:35]
	v_pk_fma_f32 v[32:33], v[96:97], s[26:27], v[32:33] op_sel_hi:[1,0,1]
	v_pk_fma_f32 v[34:35], v[98:99], s[26:27], v[34:35] op_sel_hi:[1,0,1]
	flat_store_dwordx4 v[190:191], v[32:35] offset:160
	s_nop 1
	v_mov_b64_e32 v[32:33], v[238:239]
	v_mov_b64_e32 v[34:35], v[240:241]
	v_pk_mul_f32 v[32:33], v[40:41], v[32:33]
	v_pk_mul_f32 v[34:35], v[42:43], v[34:35]
	v_pk_fma_f32 v[32:33], v[100:101], s[26:27], v[32:33] op_sel_hi:[1,0,1]
	v_pk_fma_f32 v[34:35], v[102:103], s[26:27], v[34:35] op_sel_hi:[1,0,1]
	flat_store_dwordx4 v[190:191], v[32:35] offset:192
	s_nop 1
	v_mov_b64_e32 v[32:33], v[242:243]
	v_mov_b64_e32 v[34:35], v[244:245]
	v_pk_mul_f32 v[32:33], v[44:45], v[32:33]
	v_pk_mul_f32 v[34:35], v[46:47], v[34:35]
	v_pk_fma_f32 v[32:33], v[104:105], s[26:27], v[32:33] op_sel_hi:[1,0,1]
	v_pk_fma_f32 v[34:35], v[106:107], s[26:27], v[34:35] op_sel_hi:[1,0,1]
	flat_store_dwordx4 v[190:191], v[32:35] offset:224
	s_nop 1
	v_mov_b64_e32 v[32:33], v[214:215]
	v_mov_b64_e32 v[34:35], v[216:217]
	s_nop 0
	flat_load_dwordx4 v[36:39], v[198:199] offset:3072
	flat_load_dwordx4 v[40:43], v[198:199] offset:3104
	flat_load_dwordx4 v[44:47], v[198:199] offset:3136
	flat_load_dwordx4 v[48:51], v[198:199] offset:3168
	flat_load_dwordx4 v[52:55], v[198:199] offset:3200
	flat_load_dwordx4 v[56:59], v[198:199] offset:3232
	flat_load_dwordx4 v[60:63], v[198:199] offset:3264
	flat_load_dwordx4 v[72:75], v[198:199] offset:3296
	s_waitcnt vmcnt(0) lgkmcnt(0)
	v_pk_mul_f32 v[16:17], v[16:17], v[32:33]
	v_pk_mul_f32 v[18:19], v[18:19], v[34:35]
	v_pk_fma_f32 v[16:17], v[36:37], s[26:27], v[16:17] op_sel_hi:[1,0,1]
	v_pk_fma_f32 v[18:19], v[38:39], s[26:27], v[18:19] op_sel_hi:[1,0,1]
	flat_store_dwordx4 v[76:77], v[16:19]
	s_nop 1
	v_mov_b64_e32 v[16:17], v[218:219]
	v_mov_b64_e32 v[18:19], v[220:221]
	v_pk_mul_f32 v[16:17], v[20:21], v[16:17]
	v_pk_mul_f32 v[18:19], v[22:23], v[18:19]
	v_pk_fma_f32 v[16:17], v[40:41], s[26:27], v[16:17] op_sel_hi:[1,0,1]
	v_pk_fma_f32 v[18:19], v[42:43], s[26:27], v[18:19] op_sel_hi:[1,0,1]
	flat_store_dwordx4 v[76:77], v[16:19] offset:32
	s_nop 1
	v_mov_b64_e32 v[16:17], v[222:223]
	v_mov_b64_e32 v[18:19], v[224:225]
	v_pk_mul_f32 v[16:17], v[24:25], v[16:17]
	v_pk_mul_f32 v[18:19], v[26:27], v[18:19]
	v_pk_fma_f32 v[16:17], v[44:45], s[26:27], v[16:17] op_sel_hi:[1,0,1]
	v_pk_fma_f32 v[18:19], v[46:47], s[26:27], v[18:19] op_sel_hi:[1,0,1]
	flat_store_dwordx4 v[76:77], v[16:19] offset:64
	s_nop 1
	v_mov_b64_e32 v[16:17], v[226:227]
	v_mov_b64_e32 v[18:19], v[228:229]
	v_pk_mul_f32 v[16:17], v[28:29], v[16:17]
	v_pk_mul_f32 v[18:19], v[30:31], v[18:19]
	v_pk_fma_f32 v[16:17], v[48:49], s[26:27], v[16:17] op_sel_hi:[1,0,1]
	v_pk_fma_f32 v[18:19], v[50:51], s[26:27], v[18:19] op_sel_hi:[1,0,1]
	flat_store_dwordx4 v[76:77], v[16:19] offset:96
	s_nop 1
	v_mov_b64_e32 v[16:17], v[230:231]
	v_mov_b64_e32 v[18:19], v[232:233]
	v_pk_mul_f32 v[0:1], v[0:1], v[16:17]
	v_pk_mul_f32 v[2:3], v[2:3], v[18:19]
	v_pk_fma_f32 v[0:1], v[52:53], s[26:27], v[0:1] op_sel_hi:[1,0,1]
	v_pk_fma_f32 v[2:3], v[54:55], s[26:27], v[2:3] op_sel_hi:[1,0,1]
	flat_store_dwordx4 v[76:77], v[0:3] offset:128
	s_nop 1
	v_mov_b64_e32 v[0:1], v[234:235]
	v_mov_b64_e32 v[2:3], v[236:237]
	v_pk_mul_f32 v[0:1], v[4:5], v[0:1]
	v_pk_mul_f32 v[2:3], v[6:7], v[2:3]
	v_pk_fma_f32 v[0:1], v[56:57], s[26:27], v[0:1] op_sel_hi:[1,0,1]
	v_pk_fma_f32 v[2:3], v[58:59], s[26:27], v[2:3] op_sel_hi:[1,0,1]
	flat_store_dwordx4 v[76:77], v[0:3] offset:160
	s_nop 1
	v_mov_b64_e32 v[0:1], v[238:239]
	v_mov_b64_e32 v[2:3], v[240:241]
	v_ashrrev_i32_e32 v4, 2, v213
	v_and_b32_e32 v4, -16, v4
	v_lshlrev_b32_e32 v6, 4, v213
	v_ashrrev_i32_e32 v5, 31, v4
	v_and_b32_e32 v7, 63, v213
	v_lshlrev_b64 v[4:5], 12, v[4:5]
	v_and_b32_e32 v110, 0x3f0, v6
	v_lshl_add_u64 v[16:17], s[18:19], 0, v[4:5]
	v_lshl_add_u64 v[18:19], s[20:21], 0, v[4:5]
	v_lshl_add_u64 v[20:21], s[22:23], 0, v[4:5]
	v_lshl_add_u64 v[22:23], v[64:65], 0, v[110:111]
	v_lshl_add_u64 v[24:25], v[66:67], 0, v[110:111]
	v_lshlrev_b32_e32 v110, 4, v7
	v_pk_mul_f32 v[0:1], v[8:9], v[0:1]
	v_pk_mul_f32 v[2:3], v[10:11], v[2:3]
	v_pk_fma_f32 v[0:1], v[60:61], s[26:27], v[0:1] op_sel_hi:[1,0,1]
	v_pk_fma_f32 v[2:3], v[62:63], s[26:27], v[2:3] op_sel_hi:[1,0,1]
	flat_store_dwordx4 v[76:77], v[0:3] offset:192
	s_nop 1
	v_mov_b64_e32 v[0:1], v[242:243]
	v_mov_b64_e32 v[2:3], v[244:245]
	v_lshl_add_u64 v[8:9], s[12:13], 0, v[4:5]
	v_lshl_add_u64 v[10:11], s[16:17], 0, v[4:5]
	v_pk_mul_f32 v[0:1], v[12:13], v[0:1]
	v_pk_mul_f32 v[2:3], v[14:15], v[2:3]
	v_pk_fma_f32 v[0:1], v[72:73], s[26:27], v[0:1] op_sel_hi:[1,0,1]
	v_pk_fma_f32 v[2:3], v[74:75], s[26:27], v[2:3] op_sel_hi:[1,0,1]
	flat_store_dwordx4 v[76:77], v[0:3] offset:224
	s_waitcnt lgkmcnt(0)
	s_barrier

	.amdhsa_kernel _Z4megaILin1EEv6Params
		.amdhsa_group_segment_fixed_size 73748
		.amdhsa_private_segment_fixed_size 0
		.amdhsa_kernarg_size 440
		.amdhsa_user_sgpr_count 2
		.amdhsa_user_sgpr_dispatch_ptr 0
		.amdhsa_user_sgpr_queue_ptr 0
		.amdhsa_user_sgpr_kernarg_segment_ptr 1
		.amdhsa_user_sgpr_dispatch_id 0
		.amdhsa_user_sgpr_kernarg_preload_length 0
		.amdhsa_user_sgpr_kernarg_preload_offset 0
		.amdhsa_user_sgpr_private_segment_size 0
		.amdhsa_uses_dynamic_stack 0
		.amdhsa_enable_private_segment 0
		.amdhsa_system_sgpr_workgroup_id_x 1
		.amdhsa_system_sgpr_workgroup_id_y 0
		.amdhsa_system_sgpr_workgroup_id_z 0
		.amdhsa_system_sgpr_workgroup_info 0
		.amdhsa_system_vgpr_workitem_id 2
		.amdhsa_next_free_vgpr 256
		.amdhsa_next_free_sgpr 102
		.amdhsa_accum_offset 256
		.amdhsa_reserve_vcc 1
		.amdhsa_float_round_mode_32 0
		.amdhsa_float_round_mode_16_64 0
		.amdhsa_float_denorm_mode_32 3
		.amdhsa_float_denorm_mode_16_64 3
		.amdhsa_dx10_clamp 1
		.amdhsa_ieee_mode 1
		.amdhsa_fp16_overflow 0
		.amdhsa_tg_split 0
		.amdhsa_exception_fp_ieee_invalid_op 0
		.amdhsa_exception_fp_denorm_src 0
		.amdhsa_exception_fp_ieee_div_zero 0
		.amdhsa_exception_fp_ieee_overflow 0
		.amdhsa_exception_fp_ieee_underflow 0
		.amdhsa_exception_fp_ieee_inexact 0
		.amdhsa_exception_int_div_zero 0
	.end_amdhsa_kernel

.Lfunc_end0:
	.size	_Z4megaILin1EEv6Params, .Lfunc_end0-_Z4megaILin1EEv6Params
	.set _Z4megaILin1EEv6Params.num_vgpr, 256
	.set _Z4megaILin1EEv6Params.num_agpr, 0
	.set _Z4megaILin1EEv6Params.numbered_sgpr, 102
	.set _Z4megaILin1EEv6Params.num_named_barrier, 0
	.set _Z4megaILin1EEv6Params.private_seg_size, 0
	.set _Z4megaILin1EEv6Params.uses_vcc, 1
	.set _Z4megaILin1EEv6Params.uses_flat_scratch, 0
	.set _Z4megaILin1EEv6Params.has_dyn_sized_stack, 0
	.set _Z4megaILin1EEv6Params.has_recursion, 0
	.set _Z4megaILin1EEv6Params.has_indirect_call, 0

amdhsa.kernels:
  - .agpr_count:     0
    .args:
      - .offset:         0
        .size:           184
        .value_kind:     by_value
      - .offset:         184
        .size:           4
        .value_kind:     hidden_block_count_x
      - .offset:         188
        .size:           4
        .value_kind:     hidden_block_count_y
      - .offset:         192
        .size:           4
        .value_kind:     hidden_block_count_z
      - .offset:         196
        .size:           2
        .value_kind:     hidden_group_size_x
      - .offset:         198
        .size:           2
        .value_kind:     hidden_group_size_y
      - .offset:         200
        .size:           2
        .value_kind:     hidden_group_size_z
      - .offset:         202
        .size:           2
        .value_kind:     hidden_remainder_x
      - .offset:         204
        .size:           2
        .value_kind:     hidden_remainder_y
      - .offset:         206
        .size:           2
        .value_kind:     hidden_remainder_z
      - .offset:         224
        .size:           8
        .value_kind:     hidden_global_offset_x
      - .offset:         232
        .size:           8
        .value_kind:     hidden_global_offset_y
      - .offset:         240
        .size:           8
        .value_kind:     hidden_global_offset_z
      - .offset:         248
        .size:           2
        .value_kind:     hidden_grid_dims
      - .offset:         272
        .size:           8
        .value_kind:     hidden_multigrid_sync_arg
    .group_segment_fixed_size: 73748
    .kernarg_segment_align: 8
    .kernarg_segment_size: 440
    .language:       OpenCL C
    .language_version:
      - 2
      - 0
    .max_flat_workgroup_size: 256
    .name:           _Z4megaILin1EEv6Params
    .private_segment_fixed_size: 0
    .sgpr_count:     108
    .sgpr_spill_count: 20
    .symbol:         _Z4megaILin1EEv6Params.kd
    .uniform_work_group_size: 1
    .uses_dynamic_stack: false
    .vgpr_count:     256
    .vgpr_spill_count: 0
    .wavefront_size: 64
